# K-loops: phase-1 and phase-3 vmcnt(8) waits removed (implied by the vmcnt(4) waits of phases 4 and 2), so the first MFMA segment after an epilogue overlaps the store drain
# baseline (speedup 1.0000x reference)
; #define PG8_STAGE(bufoff, gbase, voff) do { _Pragma("unroll") for (int _i = 0; _i < 2; ++_i) \
;         __builtin_amdgcn_global_load_lds((const unsigned*)((const char*)(gbase) + (voff)[_i]), (LAS unsigned*)(lds + (bufoff) + ldsw + _i * 8192), 16, 0, 0); } while (0)
; #define PG8_LDA(dst, b, h) do { _Pragma("unroll") for (int m = 0; m < 4; ++m) _Pragma("unroll") for (int k = 0; k < 2; ++k) dst[m][k] = *(const LAS bf16x8*)(lds + PG8_SA(b, h) + aoff + m * 2048 + k * 1024); } while (0)
; #define PG8_LDB(dst, b, h) do { _Pragma("unroll") for (int n = 0; n < 2; ++n) _Pragma("unroll") for (int k = 0; k < 2; ++k) dst[n][k] = *(const LAS bf16x8*)(lds + PG8_SB(b, h) + boff + n * 2048 + k * 1024); } while (0)
; #define PG8_MMA(ai, bj, At, Bt) do { __builtin_amdgcn_s_setprio(1); _Pragma("unroll") for (int m = 0; m < 4; ++m) _Pragma("unroll") for (int n = 0; n < 2; ++n) _Pragma("unroll") for (int k = 0; k < 2; ++k) \
;         acc[ai][bj][m][n] = __builtin_amdgcn_mfma_f32_16x16x32_bf16(Bt[n][k], At[m][k], acc[ai][bj][m][n], 0, 0, 0); __builtin_amdgcn_s_setprio(0); } while (0)
; #define PG8_WAIT_V(n) asm volatile("s_waitcnt vmcnt(" #n ")" ::: "memory")
; #define PG8_WAIT_L(n) asm volatile("s_waitcnt lgkmcnt(" #n ")" ::: "memory")
; #define PG8_BAR __builtin_amdgcn_s_barrier()
; #define PG8_SCHED __builtin_amdgcn_sched_barrier(0)
; template <class Epi, bool ALIGN_EPI>
; __device__ __forceinline__ void gemm_phase(LAS unsigned char* lds, const int tid, const Gemm g, const StaticOrder& S, const Epi& E) {
;     ...
;             PG8_LDB(B0, 0, 0); PG8_LDB(B1, 0, 1); PG8_SCHED; PG8_LDA(At, 0, 0); PG8_STAGE(PG8_SA(1, 1), a1 + hstepA, voffA);
;             PG8_WAIT_V(8); PG8_WAIT_L(0); PG8_BAR; PG8_MMA(0, 0, At, B0); PG8_MMA(0, 1, At, B1); PG8_BAR; PG8_SCHED;
;             PG8_LDA(At, 0, 1); PG8_STAGE(PG8_SB(0, 0), b2, voffB); PG8_STAGE(PG8_SB(0, 1), b2 + hstepB, voffB); PG8_STAGE(PG8_SA(0, 0), a2, voffA);
;             PG8_WAIT_V(8); PG8_WAIT_L(0); PG8_BAR; PG8_MMA(1, 0, At, B0); PG8_MMA(1, 1, At, B1); PG8_BAR; PG8_SCHED;
.LBB0_113:
	s_add_i32 s90, s90, 2
	s_and_b64 s[34:35], exec, s[34:35]
	s_cselect_b32 s55, s23, s27
	s_cselect_b32 s54, s22, s25
	s_add_u32 s34, s92, 0x120000
	s_addc_u32 s35, s93, 0
	s_add_i32 s91, 0, 0x10000
	s_add_i32 s96, 0, 0x14000
	v_add_u32_e32 v148, s91, v175
	v_add_u32_e32 v164, s96, v175
	ds_read_b128 v[136:139], v148
	ds_read_b128 v[140:143], v148 offset:1024
	ds_read_b128 v[144:147], v148 offset:2048
	ds_read_b128 v[148:151], v148 offset:3072
	ds_read_b128 v[152:155], v164
	ds_read_b128 v[156:159], v164 offset:1024
	ds_read_b128 v[160:163], v164 offset:2048
	ds_read_b128 v[164:167], v164 offset:3072
	v_lshl_add_u64 v[172:173], s[30:31], 0, v[134:135]
	s_add_i32 m0, s56, 0xc000
	ds_read_b128 v[168:171], v177
	ds_read_b128 v[178:181], v177 offset:1024
	ds_read_b128 v[182:185], v177 offset:2048
	ds_read_b128 v[186:189], v177 offset:3072
	ds_read_b128 v[190:193], v177 offset:4096
	ds_read_b128 v[210:213], v177 offset:5120
	ds_read_b128 v[214:217], v177 offset:6144
	ds_read_b128 v[218:221], v177 offset:7168
	global_load_lds_dwordx4 v[172:173], off
	v_lshl_add_u64 v[172:173], s[30:31], 0, v[132:133]
	s_add_i32 m0, s56, 0xe000
	s_nop 0
	global_load_lds_dwordx4 v[172:173], off
	s_sub_u32 s98, s30, 0x4000
	s_subb_u32 s99, s31, 0
	v_lshl_add_u64 v[172:173], s[98:99], 0, v[134:135]
	s_mov_b32 m0, s70
	s_nop 0
	global_load_lds_dwordx4 v[172:173], off
	v_lshl_add_u64 v[172:173], s[98:99], 0, v[132:133]
	s_mov_b32 m0, s71
	s_nop 0
	global_load_lds_dwordx4 v[172:173], off
	s_nop 0
	s_waitcnt lgkmcnt(0)
	s_barrier
	v_mfma_f32_16x16x32_bf16 v[126:129], v[136:139], v[168:171], v[126:129]
	v_mfma_f32_16x16x32_bf16 v[94:97], v[144:147], v[168:171], v[94:97]
	v_mfma_f32_16x16x32_bf16 v[122:125], v[136:139], v[182:185], v[122:125]
	v_mfma_f32_16x16x32_bf16 v[90:93], v[144:147], v[182:185], v[90:93]
	v_mfma_f32_16x16x32_bf16 v[118:121], v[136:139], v[190:193], v[118:121]
	v_mfma_f32_16x16x32_bf16 v[86:89], v[144:147], v[190:193], v[86:89]
	v_mfma_f32_16x16x32_bf16 v[114:117], v[136:139], v[214:217], v[114:117]
	v_mfma_f32_16x16x32_bf16 v[82:85], v[144:147], v[214:217], v[82:85]
	v_mfma_f32_16x16x32_bf16 v[126:129], v[140:143], v[178:181], v[126:129]
	v_mfma_f32_16x16x32_bf16 v[94:97], v[148:151], v[178:181], v[94:97]
	v_mfma_f32_16x16x32_bf16 v[122:125], v[140:143], v[186:189], v[122:125]
	v_mfma_f32_16x16x32_bf16 v[90:93], v[148:151], v[186:189], v[90:93]
	v_mfma_f32_16x16x32_bf16 v[118:121], v[140:143], v[210:213], v[118:121]
	v_mfma_f32_16x16x32_bf16 v[86:89], v[148:151], v[210:213], v[86:89]
	v_mfma_f32_16x16x32_bf16 v[114:117], v[140:143], v[218:221], v[114:117]
	v_mfma_f32_16x16x32_bf16 v[82:85], v[148:151], v[218:221], v[82:85]
	v_mfma_f32_16x16x32_bf16 v[62:65], v[152:155], v[168:171], v[62:65]
	v_mfma_f32_16x16x32_bf16 v[38:41], v[160:163], v[168:171], v[38:41]
	v_mfma_f32_16x16x32_bf16 v[58:61], v[152:155], v[182:185], v[58:61]
	v_mfma_f32_16x16x32_bf16 v[30:33], v[160:163], v[182:185], v[30:33]
	v_mfma_f32_16x16x32_bf16 v[54:57], v[152:155], v[190:193], v[54:57]
	v_mfma_f32_16x16x32_bf16 v[22:25], v[160:163], v[190:193], v[22:25]
	v_mfma_f32_16x16x32_bf16 v[50:53], v[152:155], v[214:217], v[50:53]
	v_mfma_f32_16x16x32_bf16 v[18:21], v[160:163], v[214:217], v[18:21]
	v_mfma_f32_16x16x32_bf16 v[62:65], v[156:159], v[178:181], v[62:65]
	v_mfma_f32_16x16x32_bf16 v[38:41], v[164:167], v[178:181], v[38:41]
	v_mfma_f32_16x16x32_bf16 v[58:61], v[156:159], v[186:189], v[58:61]
	v_mfma_f32_16x16x32_bf16 v[30:33], v[164:167], v[186:189], v[30:33]
	v_mfma_f32_16x16x32_bf16 v[54:57], v[156:159], v[210:213], v[54:57]
	v_mfma_f32_16x16x32_bf16 v[22:25], v[164:167], v[210:213], v[22:25]
	v_mfma_f32_16x16x32_bf16 v[50:53], v[156:159], v[218:221], v[50:53]
	v_mfma_f32_16x16x32_bf16 v[18:21], v[164:167], v[218:221], v[18:21]
	s_barrier
	s_add_i32 s91, s91, s29
	v_lshl_add_u64 v[172:173], s[54:55], 0, v[0:1]
	s_mov_b32 m0, s91
	ds_read_b128 v[168:171], v177 offset:16384
	ds_read_b128 v[178:181], v177 offset:17408
	ds_read_b128 v[182:185], v177 offset:18432
	ds_read_b128 v[186:189], v177 offset:19456
	ds_read_b128 v[190:193], v177 offset:20480
	ds_read_b128 v[210:213], v177 offset:21504
	ds_read_b128 v[214:217], v177 offset:22528
	ds_read_b128 v[218:221], v177 offset:23552
	global_load_lds_dwordx4 v[172:173], off
	s_add_i32 m0, s91, 0x2000
	s_add_u32 s94, s54, 0x4000
	v_lshl_add_u64 v[172:173], s[54:55], 0, v[130:131]
	s_addc_u32 s95, s55, 0
	s_add_i32 s91, s96, s29
	global_load_lds_dwordx4 v[172:173], off
	v_lshl_add_u64 v[172:173], s[94:95], 0, v[0:1]
	s_mov_b32 m0, s91
	s_nop 0
	global_load_lds_dwordx4 v[172:173], off
	v_lshl_add_u64 v[172:173], s[94:95], 0, v[130:131]
	s_add_i32 m0, s91, 0x2000
	s_nop 0
	global_load_lds_dwordx4 v[172:173], off
	s_waitcnt vmcnt(4)
	s_waitcnt lgkmcnt(0)
	s_barrier
; #define PG8_STAGE(bufoff, gbase, voff) do { _Pragma("unroll") for (int _i = 0; _i < 2; ++_i) \
;         __builtin_amdgcn_global_load_lds((const unsigned*)((const char*)(gbase) + (voff)[_i]), (LAS unsigned*)(lds + (bufoff) + ldsw + _i * 8192), 16, 0, 0); } while (0)
; #define PG8_LDA(dst, b, h) do { _Pragma("unroll") for (int m = 0; m < 4; ++m) _Pragma("unroll") for (int k = 0; k < 2; ++k) dst[m][k] = *(const LAS bf16x8*)(lds + PG8_SA(b, h) + aoff + m * 2048 + k * 1024); } while (0)
; #define PG8_LDB(dst, b, h) do { _Pragma("unroll") for (int n = 0; n < 2; ++n) _Pragma("unroll") for (int k = 0; k < 2; ++k) dst[n][k] = *(const LAS bf16x8*)(lds + PG8_SB(b, h) + boff + n * 2048 + k * 1024); } while (0)
; #define PG8_MMA(ai, bj, At, Bt) do { __builtin_amdgcn_s_setprio(1); _Pragma("unroll") for (int m = 0; m < 4; ++m) _Pragma("unroll") for (int n = 0; n < 2; ++n) _Pragma("unroll") for (int k = 0; k < 2; ++k) \
;         acc[ai][bj][m][n] = __builtin_amdgcn_mfma_f32_16x16x32_bf16(Bt[n][k], At[m][k], acc[ai][bj][m][n], 0, 0, 0); __builtin_amdgcn_s_setprio(0); } while (0)
; #define PG8_WAIT_V(n) asm volatile("s_waitcnt vmcnt(" #n ")" ::: "memory")
; #define PG8_WAIT_L(n) asm volatile("s_waitcnt lgkmcnt(" #n ")" ::: "memory")
; #define PG8_BAR __builtin_amdgcn_s_barrier()
; #define PG8_SCHED __builtin_amdgcn_sched_barrier(0)
; template <class Epi, bool ALIGN_EPI>
; __device__ __forceinline__ void gemm_phase(LAS unsigned char* lds, const int tid, const Gemm g, const StaticOrder& S, const Epi& E) {
;     ...
;             PG8_WAIT_V(8); PG8_WAIT_L(0); PG8_BAR; PG8_MMA(1, 0, At, B0); PG8_MMA(1, 1, At, B1); PG8_BAR; PG8_SCHED;
;             PG8_LDB(B0, 1, 0); PG8_LDB(B1, 1, 1); PG8_SCHED; PG8_LDA(At, 1, 0); PG8_STAGE(PG8_SA(0, 1), a2 + hstepA, voffA);
;             PG8_WAIT_V(8); PG8_WAIT_L(0); PG8_BAR; PG8_MMA(0, 0, At, B0); PG8_MMA(0, 1, At, B1); PG8_BAR; PG8_SCHED;
	v_mfma_f32_16x16x32_bf16 v[110:113], v[136:139], v[168:171], v[110:113]
	v_mfma_f32_16x16x32_bf16 v[78:81], v[144:147], v[168:171], v[78:81]
	v_mfma_f32_16x16x32_bf16 v[106:109], v[136:139], v[182:185], v[106:109]
	v_mfma_f32_16x16x32_bf16 v[74:77], v[144:147], v[182:185], v[74:77]
	v_mfma_f32_16x16x32_bf16 v[102:105], v[136:139], v[190:193], v[102:105]
	v_mfma_f32_16x16x32_bf16 v[70:73], v[144:147], v[190:193], v[70:73]
	v_mfma_f32_16x16x32_bf16 v[98:101], v[136:139], v[214:217], v[98:101]
	v_mfma_f32_16x16x32_bf16 v[66:69], v[144:147], v[214:217], v[66:69]
	v_mfma_f32_16x16x32_bf16 v[110:113], v[140:143], v[178:181], v[110:113]
	v_mfma_f32_16x16x32_bf16 v[78:81], v[148:151], v[178:181], v[78:81]
	v_mfma_f32_16x16x32_bf16 v[106:109], v[140:143], v[186:189], v[106:109]
	v_mfma_f32_16x16x32_bf16 v[74:77], v[148:151], v[186:189], v[74:77]
	v_mfma_f32_16x16x32_bf16 v[102:105], v[140:143], v[210:213], v[102:105]
	v_mfma_f32_16x16x32_bf16 v[70:73], v[148:151], v[210:213], v[70:73]
	v_mfma_f32_16x16x32_bf16 v[98:101], v[140:143], v[218:221], v[98:101]
	v_mfma_f32_16x16x32_bf16 v[66:69], v[148:151], v[218:221], v[66:69]
	v_mfma_f32_16x16x32_bf16 v[46:49], v[152:155], v[168:171], v[46:49]
	v_mfma_f32_16x16x32_bf16 v[14:17], v[160:163], v[168:171], v[14:17]
	v_mfma_f32_16x16x32_bf16 v[42:45], v[152:155], v[182:185], v[42:45]
	v_mfma_f32_16x16x32_bf16 v[10:13], v[160:163], v[182:185], v[10:13]
	v_mfma_f32_16x16x32_bf16 v[34:37], v[152:155], v[190:193], v[34:37]
	v_mfma_f32_16x16x32_bf16 v[6:9], v[160:163], v[190:193], v[6:9]
	v_mfma_f32_16x16x32_bf16 v[26:29], v[152:155], v[214:217], v[26:29]
	v_mfma_f32_16x16x32_bf16 v[2:5], v[160:163], v[214:217], v[2:5]
	v_mfma_f32_16x16x32_bf16 v[46:49], v[156:159], v[178:181], v[46:49]
	v_mfma_f32_16x16x32_bf16 v[14:17], v[164:167], v[178:181], v[14:17]
	v_mfma_f32_16x16x32_bf16 v[42:45], v[156:159], v[186:189], v[42:45]
	v_mfma_f32_16x16x32_bf16 v[10:13], v[164:167], v[186:189], v[10:13]
	v_mfma_f32_16x16x32_bf16 v[34:37], v[156:159], v[210:213], v[34:37]
	v_mfma_f32_16x16x32_bf16 v[6:9], v[164:167], v[210:213], v[6:9]
	v_mfma_f32_16x16x32_bf16 v[26:29], v[156:159], v[218:221], v[26:29]
	v_mfma_f32_16x16x32_bf16 v[2:5], v[164:167], v[218:221], v[2:5]
	s_barrier
	s_add_i32 s91, 0, 0x18000
	s_add_i32 s94, 0, 0x1c000
	v_add_u32_e32 v148, s91, v175
	v_add_u32_e32 v164, s94, v175
	ds_read_b128 v[136:139], v148
	ds_read_b128 v[140:143], v148 offset:1024
	ds_read_b128 v[144:147], v148 offset:2048
	ds_read_b128 v[148:151], v148 offset:3072
	ds_read_b128 v[152:155], v164
	ds_read_b128 v[156:159], v164 offset:1024
	ds_read_b128 v[160:163], v164 offset:2048
	ds_read_b128 v[164:167], v164 offset:3072
	v_lshl_add_u64 v[172:173], s[92:93], 0, v[0:1]
	s_mov_b32 m0, s56
	s_nop 0
	global_load_lds_dwordx4 v[172:173], off
	v_lshl_add_u64 v[172:173], s[92:93], 0, v[130:131]
	s_mov_b32 m0, s58
	s_nop 0
	global_load_lds_dwordx4 v[172:173], off
	s_add_u32 s92, s92, 0x4000
	s_addc_u32 s93, s93, 0
	s_mov_b32 m0, s63
	v_lshl_add_u64 v[172:173], s[92:93], 0, v[0:1]
	ds_read_b128 v[168:171], v177 offset:32768
	ds_read_b128 v[178:181], v177 offset:33792
	ds_read_b128 v[182:185], v177 offset:34816
	ds_read_b128 v[186:189], v177 offset:35840
	ds_read_b128 v[190:193], v177 offset:36864
	ds_read_b128 v[210:213], v177 offset:37888
	ds_read_b128 v[214:217], v177 offset:38912
	ds_read_b128 v[218:221], v177 offset:39936
	global_load_lds_dwordx4 v[172:173], off
	v_lshl_add_u64 v[172:173], s[92:93], 0, v[130:131]
	s_mov_b32 m0, s64
	s_nop 0
	global_load_lds_dwordx4 v[172:173], off
	s_nop 0
	s_waitcnt lgkmcnt(0)
	s_barrier
; #define PG8_STAGE(bufoff, gbase, voff) do { _Pragma("unroll") for (int _i = 0; _i < 2; ++_i) \
;         __builtin_amdgcn_global_load_lds((const unsigned*)((const char*)(gbase) + (voff)[_i]), (LAS unsigned*)(lds + (bufoff) + ldsw + _i * 8192), 16, 0, 0); } while (0)
; #define PG8_LDA(dst, b, h) do { _Pragma("unroll") for (int m = 0; m < 4; ++m) _Pragma("unroll") for (int k = 0; k < 2; ++k) dst[m][k] = *(const LAS bf16x8*)(lds + PG8_SA(b, h) + aoff + m * 2048 + k * 1024); } while (0)
; #define PG8_MMA(ai, bj, At, Bt) do { __builtin_amdgcn_s_setprio(1); _Pragma("unroll") for (int m = 0; m < 4; ++m) _Pragma("unroll") for (int n = 0; n < 2; ++n) _Pragma("unroll") for (int k = 0; k < 2; ++k) \
;         acc[ai][bj][m][n] = __builtin_amdgcn_mfma_f32_16x16x32_bf16(Bt[n][k], At[m][k], acc[ai][bj][m][n], 0, 0, 0); __builtin_amdgcn_s_setprio(0); } while (0)
; #define PG8_WAIT_V(n) asm volatile("s_waitcnt vmcnt(" #n ")" ::: "memory")
; #define PG8_WAIT_L(n) asm volatile("s_waitcnt lgkmcnt(" #n ")" ::: "memory")
; #define PG8_BAR __builtin_amdgcn_s_barrier()
; #define PG8_SCHED __builtin_amdgcn_sched_barrier(0)
; template <class Epi, bool ALIGN_EPI>
; __device__ __forceinline__ void gemm_phase(LAS unsigned char* lds, const int tid, const Gemm g, const StaticOrder& S, const Epi& E) {
;     ...
;             PG8_WAIT_V(8); PG8_WAIT_L(0); PG8_BAR; PG8_MMA(0, 0, At, B0); PG8_MMA(0, 1, At, B1); PG8_BAR; PG8_SCHED;
;             PG8_LDA(At, 1, 1); PG8_STAGE(PG8_SB(1, 0), b3, voffB); PG8_STAGE(PG8_SB(1, 1), b3 + hstepB, voffB); PG8_STAGE(PG8_SA(1, 0), a3, voffA);
;             PG8_WAIT_V(8); PG8_WAIT_L(0); PG8_BAR; PG8_MMA(1, 0, At, B0); PG8_MMA(1, 1, At, B1); PG8_BAR; PG8_SCHED;
;         }
	v_mfma_f32_16x16x32_bf16 v[126:129], v[136:139], v[168:171], v[126:129]
	v_mfma_f32_16x16x32_bf16 v[94:97], v[144:147], v[168:171], v[94:97]
	v_mfma_f32_16x16x32_bf16 v[122:125], v[136:139], v[182:185], v[122:125]
	v_mfma_f32_16x16x32_bf16 v[90:93], v[144:147], v[182:185], v[90:93]
	v_mfma_f32_16x16x32_bf16 v[118:121], v[136:139], v[190:193], v[118:121]
	v_mfma_f32_16x16x32_bf16 v[86:89], v[144:147], v[190:193], v[86:89]
	v_mfma_f32_16x16x32_bf16 v[114:117], v[136:139], v[214:217], v[114:117]
	v_mfma_f32_16x16x32_bf16 v[82:85], v[144:147], v[214:217], v[82:85]
	v_mfma_f32_16x16x32_bf16 v[126:129], v[140:143], v[178:181], v[126:129]
	v_mfma_f32_16x16x32_bf16 v[94:97], v[148:151], v[178:181], v[94:97]
	v_mfma_f32_16x16x32_bf16 v[122:125], v[140:143], v[186:189], v[122:125]
	v_mfma_f32_16x16x32_bf16 v[90:93], v[148:151], v[186:189], v[90:93]
	v_mfma_f32_16x16x32_bf16 v[118:121], v[140:143], v[210:213], v[118:121]
	v_mfma_f32_16x16x32_bf16 v[86:89], v[148:151], v[210:213], v[86:89]
	v_mfma_f32_16x16x32_bf16 v[114:117], v[140:143], v[218:221], v[114:117]
	v_mfma_f32_16x16x32_bf16 v[82:85], v[148:151], v[218:221], v[82:85]
	v_mfma_f32_16x16x32_bf16 v[62:65], v[152:155], v[168:171], v[62:65]
	v_mfma_f32_16x16x32_bf16 v[38:41], v[160:163], v[168:171], v[38:41]
	v_mfma_f32_16x16x32_bf16 v[58:61], v[152:155], v[182:185], v[58:61]
	v_mfma_f32_16x16x32_bf16 v[30:33], v[160:163], v[182:185], v[30:33]
	v_mfma_f32_16x16x32_bf16 v[54:57], v[152:155], v[190:193], v[54:57]
	v_mfma_f32_16x16x32_bf16 v[22:25], v[160:163], v[190:193], v[22:25]
	v_mfma_f32_16x16x32_bf16 v[50:53], v[152:155], v[214:217], v[50:53]
	v_mfma_f32_16x16x32_bf16 v[18:21], v[160:163], v[214:217], v[18:21]
	v_mfma_f32_16x16x32_bf16 v[62:65], v[156:159], v[178:181], v[62:65]
	v_mfma_f32_16x16x32_bf16 v[38:41], v[164:167], v[178:181], v[38:41]
	v_mfma_f32_16x16x32_bf16 v[58:61], v[156:159], v[186:189], v[58:61]
	v_mfma_f32_16x16x32_bf16 v[30:33], v[164:167], v[186:189], v[30:33]
	v_mfma_f32_16x16x32_bf16 v[54:57], v[156:159], v[210:213], v[54:57]
	v_mfma_f32_16x16x32_bf16 v[22:25], v[164:167], v[210:213], v[22:25]
	v_mfma_f32_16x16x32_bf16 v[50:53], v[156:159], v[218:221], v[50:53]
	v_mfma_f32_16x16x32_bf16 v[18:21], v[164:167], v[218:221], v[18:21]
	s_barrier
	s_add_u32 s92, s54, 0x40000
	s_addc_u32 s93, s55, 0
	s_add_i32 s91, s91, s29
	v_lshl_add_u64 v[172:173], s[92:93], 0, v[0:1]
	s_mov_b32 m0, s91
	ds_read_b128 v[168:171], v177 offset:49152
	ds_read_b128 v[178:181], v177 offset:50176
	ds_read_b128 v[182:185], v177 offset:51200
	ds_read_b128 v[186:189], v177 offset:52224
	ds_read_b128 v[190:193], v177 offset:53248
	ds_read_b128 v[210:213], v177 offset:54272
	ds_read_b128 v[214:217], v177 offset:55296
	ds_read_b128 v[218:221], v177 offset:56320
	global_load_lds_dwordx4 v[172:173], off
	s_add_i32 m0, s91, 0x2000
	s_add_u32 s54, s54, 0x44000
	v_lshl_add_u64 v[172:173], s[92:93], 0, v[130:131]
	s_addc_u32 s55, s55, 0
	s_add_i32 s91, s94, s29
	global_load_lds_dwordx4 v[172:173], off
	v_lshl_add_u64 v[172:173], s[54:55], 0, v[0:1]
	s_mov_b32 m0, s91
	s_nop 0
	global_load_lds_dwordx4 v[172:173], off
	v_lshl_add_u64 v[172:173], s[54:55], 0, v[130:131]
	s_add_i32 m0, s91, 0x2000
	s_nop 0
	global_load_lds_dwordx4 v[172:173], off
	s_waitcnt vmcnt(4)
	s_waitcnt lgkmcnt(0)
	s_barrier
	v_mfma_f32_16x16x32_bf16 v[110:113], v[136:139], v[168:171], v[110:113]
	v_mfma_f32_16x16x32_bf16 v[78:81], v[144:147], v[168:171], v[78:81]
	v_mfma_f32_16x16x32_bf16 v[106:109], v[136:139], v[182:185], v[106:109]
	v_mfma_f32_16x16x32_bf16 v[74:77], v[144:147], v[182:185], v[74:77]
	v_mfma_f32_16x16x32_bf16 v[102:105], v[136:139], v[190:193], v[102:105]
	v_mfma_f32_16x16x32_bf16 v[70:73], v[144:147], v[190:193], v[70:73]
	v_mfma_f32_16x16x32_bf16 v[98:101], v[136:139], v[214:217], v[98:101]
	v_mfma_f32_16x16x32_bf16 v[66:69], v[144:147], v[214:217], v[66:69]
	v_mfma_f32_16x16x32_bf16 v[110:113], v[140:143], v[178:181], v[110:113]
	v_mfma_f32_16x16x32_bf16 v[78:81], v[148:151], v[178:181], v[78:81]
	v_mfma_f32_16x16x32_bf16 v[106:109], v[140:143], v[186:189], v[106:109]
	v_mfma_f32_16x16x32_bf16 v[74:77], v[148:151], v[186:189], v[74:77]
	v_mfma_f32_16x16x32_bf16 v[102:105], v[140:143], v[210:213], v[102:105]
	v_mfma_f32_16x16x32_bf16 v[70:73], v[148:151], v[210:213], v[70:73]
	v_mfma_f32_16x16x32_bf16 v[98:101], v[140:143], v[218:221], v[98:101]
	v_mfma_f32_16x16x32_bf16 v[66:69], v[148:151], v[218:221], v[66:69]
	v_mfma_f32_16x16x32_bf16 v[46:49], v[152:155], v[168:171], v[46:49]
	v_mfma_f32_16x16x32_bf16 v[14:17], v[160:163], v[168:171], v[14:17]
	v_mfma_f32_16x16x32_bf16 v[42:45], v[152:155], v[182:185], v[42:45]
	v_mfma_f32_16x16x32_bf16 v[10:13], v[160:163], v[182:185], v[10:13]
	v_mfma_f32_16x16x32_bf16 v[34:37], v[152:155], v[190:193], v[34:37]
	v_mfma_f32_16x16x32_bf16 v[6:9], v[160:163], v[190:193], v[6:9]
	v_mfma_f32_16x16x32_bf16 v[26:29], v[152:155], v[214:217], v[26:29]
	v_mfma_f32_16x16x32_bf16 v[2:5], v[160:163], v[214:217], v[2:5]
	v_mfma_f32_16x16x32_bf16 v[46:49], v[156:159], v[178:181], v[46:49]
	v_mfma_f32_16x16x32_bf16 v[14:17], v[164:167], v[178:181], v[14:17]
	v_mfma_f32_16x16x32_bf16 v[42:45], v[156:159], v[186:189], v[42:45]
	v_mfma_f32_16x16x32_bf16 v[10:13], v[164:167], v[186:189], v[10:13]
	v_mfma_f32_16x16x32_bf16 v[34:37], v[156:159], v[210:213], v[34:37]
	v_mfma_f32_16x16x32_bf16 v[6:9], v[164:167], v[210:213], v[6:9]
	v_mfma_f32_16x16x32_bf16 v[26:29], v[156:159], v[218:221], v[26:29]
	v_mfma_f32_16x16x32_bf16 v[2:5], v[164:167], v[218:221], v[2:5]
	s_barrier
	s_add_u32 s25, s25, 0x80000
	s_addc_u32 s27, s27, 0
	s_add_u32 s30, s30, 0x240000
	s_addc_u32 s31, s31, 0
	s_cmp_ge_u32 s90, s17
	s_cbranch_scc1 .LBB0_116

; #define PG8_STAGE(bufoff, gbase, voff) do { _Pragma("unroll") for (int _i = 0; _i < 2; ++_i) \
;         __builtin_amdgcn_global_load_lds((const unsigned*)((const char*)(gbase) + (voff)[_i]), (LAS unsigned*)(lds + (bufoff) + ldsw + _i * 8192), 16, 0, 0); } while (0)
; #define PG8_LDA(dst, b, h) do { _Pragma("unroll") for (int m = 0; m < 4; ++m) _Pragma("unroll") for (int k = 0; k < 2; ++k) dst[m][k] = *(const LAS bf16x8*)(lds + PG8_SA(b, h) + aoff + m * 2048 + k * 1024); } while (0)
; #define PG8_LDB(dst, b, h) do { _Pragma("unroll") for (int n = 0; n < 2; ++n) _Pragma("unroll") for (int k = 0; k < 2; ++k) dst[n][k] = *(const LAS bf16x8*)(lds + PG8_SB(b, h) + boff + n * 2048 + k * 1024); } while (0)
; #define PG8_MMA(ai, bj, At, Bt) do { __builtin_amdgcn_s_setprio(1); _Pragma("unroll") for (int m = 0; m < 4; ++m) _Pragma("unroll") for (int n = 0; n < 2; ++n) _Pragma("unroll") for (int k = 0; k < 2; ++k) \
;         acc[ai][bj][m][n] = __builtin_amdgcn_mfma_f32_16x16x32_bf16(Bt[n][k], At[m][k], acc[ai][bj][m][n], 0, 0, 0); __builtin_amdgcn_s_setprio(0); } while (0)
; #define PG8_WAIT_V(n) asm volatile("s_waitcnt vmcnt(" #n ")" ::: "memory")
; #define PG8_WAIT_L(n) asm volatile("s_waitcnt lgkmcnt(" #n ")" ::: "memory")
; #define PG8_BAR __builtin_amdgcn_s_barrier()
; #define PG8_SCHED __builtin_amdgcn_sched_barrier(0)
; template <class Epi, bool ALIGN_EPI>
; __device__ __forceinline__ void gemm_phase(LAS unsigned char* lds, const int tid, const Gemm g, const StaticOrder& S, const Epi& E) {
;     ...
;             PG8_LDB(B0, 0, 0); PG8_LDB(B1, 0, 1); PG8_SCHED; PG8_LDA(At, 0, 0); PG8_STAGE(PG8_SA(1, 1), a1 + hstepA, voffA);
;             PG8_WAIT_V(8); PG8_WAIT_L(0); PG8_BAR; PG8_MMA(0, 0, At, B0); PG8_MMA(0, 1, At, B1); PG8_BAR; PG8_SCHED;
;             PG8_LDA(At, 0, 1); PG8_STAGE(PG8_SB(0, 0), b2, voffB); PG8_STAGE(PG8_SB(0, 1), b2 + hstepB, voffB); PG8_STAGE(PG8_SA(0, 0), a2, voffA);
;             PG8_WAIT_V(8); PG8_WAIT_L(0); PG8_BAR; PG8_MMA(1, 0, At, B0); PG8_MMA(1, 1, At, B1); PG8_BAR; PG8_SCHED;
.LBB0_143:
	s_add_u32 s26, s24, 0xfff80080
	s_addc_u32 s27, s25, -1
	s_add_i32 s68, 0, 0x10000
	s_cmp_eq_u32 s67, 28
	s_cselect_b32 s29, s19, s27
	s_cselect_b32 s28, s18, s26
	v_add_u32_e32 v142, s68, v145
	s_cselect_b32 s27, s21, s17
	s_cselect_b32 s26, s20, s15
	s_add_i32 s70, 0, 0x14000
	ds_read_b128 v[148:151], v142
	ds_read_b128 v[152:155], v142 offset:1024
	ds_read_b128 v[156:159], v142 offset:2048
	ds_read_b128 v[160:163], v142 offset:3072
	v_add_u32_e32 v142, s70, v145
	ds_read_b128 v[164:167], v142
	ds_read_b128 v[168:171], v142 offset:1024
	ds_read_b128 v[172:175], v142 offset:2048
	ds_read_b128 v[176:179], v142 offset:3072
	v_lshl_add_u64 v[142:143], s[24:25], 0, v[140:141]
	s_add_i32 m0, s23, 0xc000
	ds_read_b128 v[180:183], v146
	ds_read_b128 v[184:187], v146 offset:1024
	ds_read_b128 v[188:191], v146 offset:2048
	ds_read_b128 v[192:195], v146 offset:3072
	ds_read_b128 v[210:213], v146 offset:4096
	ds_read_b128 v[214:217], v146 offset:5120
	ds_read_b128 v[218:221], v146 offset:6144
	ds_read_b128 v[222:225], v146 offset:7168
	global_load_lds_dwordx4 v[142:143], off
	v_lshl_add_u64 v[142:143], s[24:25], 0, v[138:139]
	s_add_i32 m0, s23, 0xe000
	s_nop 0
	global_load_lds_dwordx4 v[142:143], off
	s_sub_u32 s98, s24, 0x80000
	s_subb_u32 s99, s25, 0
	v_lshl_add_u64 v[142:143], s[98:99], 0, v[140:141]
	s_mov_b32 m0, s56
	s_nop 0
	global_load_lds_dwordx4 v[142:143], off
	v_lshl_add_u64 v[142:143], s[98:99], 0, v[138:139]
	s_mov_b32 m0, s58
	s_nop 0
	global_load_lds_dwordx4 v[142:143], off
	s_nop 0
	s_waitcnt lgkmcnt(0)
	s_barrier
	v_mfma_f32_16x16x32_bf16 v[126:129], v[148:151], v[180:183], v[126:129]
	v_mfma_f32_16x16x32_bf16 v[122:125], v[156:159], v[180:183], v[122:125]
	v_mfma_f32_16x16x32_bf16 v[110:113], v[148:151], v[188:191], v[110:113]
	v_mfma_f32_16x16x32_bf16 v[106:109], v[156:159], v[188:191], v[106:109]
	v_mfma_f32_16x16x32_bf16 v[94:97], v[148:151], v[210:213], v[94:97]
	v_mfma_f32_16x16x32_bf16 v[90:93], v[156:159], v[210:213], v[90:93]
	v_mfma_f32_16x16x32_bf16 v[78:81], v[148:151], v[218:221], v[78:81]
	v_mfma_f32_16x16x32_bf16 v[74:77], v[156:159], v[218:221], v[74:77]
	v_mfma_f32_16x16x32_bf16 v[126:129], v[152:155], v[184:187], v[126:129]
	v_mfma_f32_16x16x32_bf16 v[122:125], v[160:163], v[184:187], v[122:125]
	v_mfma_f32_16x16x32_bf16 v[110:113], v[152:155], v[192:195], v[110:113]
	v_mfma_f32_16x16x32_bf16 v[106:109], v[160:163], v[192:195], v[106:109]
	v_mfma_f32_16x16x32_bf16 v[94:97], v[152:155], v[214:217], v[94:97]
	v_mfma_f32_16x16x32_bf16 v[90:93], v[160:163], v[214:217], v[90:93]
	v_mfma_f32_16x16x32_bf16 v[78:81], v[152:155], v[222:225], v[78:81]
	v_mfma_f32_16x16x32_bf16 v[74:77], v[160:163], v[222:225], v[74:77]
	v_mfma_f32_16x16x32_bf16 v[118:121], v[164:167], v[180:183], v[118:121]
	v_mfma_f32_16x16x32_bf16 v[114:117], v[172:175], v[180:183], v[114:117]
	v_mfma_f32_16x16x32_bf16 v[102:105], v[164:167], v[188:191], v[102:105]
	v_mfma_f32_16x16x32_bf16 v[98:101], v[172:175], v[188:191], v[98:101]
	v_mfma_f32_16x16x32_bf16 v[86:89], v[164:167], v[210:213], v[86:89]
	v_mfma_f32_16x16x32_bf16 v[82:85], v[172:175], v[210:213], v[82:85]
	v_mfma_f32_16x16x32_bf16 v[70:73], v[164:167], v[218:221], v[70:73]
	v_mfma_f32_16x16x32_bf16 v[66:69], v[172:175], v[218:221], v[66:69]
	v_mfma_f32_16x16x32_bf16 v[118:121], v[168:171], v[184:187], v[118:121]
	v_mfma_f32_16x16x32_bf16 v[114:117], v[176:179], v[184:187], v[114:117]
	v_mfma_f32_16x16x32_bf16 v[102:105], v[168:171], v[192:195], v[102:105]
	v_mfma_f32_16x16x32_bf16 v[98:101], v[176:179], v[192:195], v[98:101]
	v_mfma_f32_16x16x32_bf16 v[86:89], v[168:171], v[214:217], v[86:89]
	v_mfma_f32_16x16x32_bf16 v[82:85], v[176:179], v[214:217], v[82:85]
	v_mfma_f32_16x16x32_bf16 v[70:73], v[168:171], v[222:225], v[70:73]
	v_mfma_f32_16x16x32_bf16 v[66:69], v[176:179], v[222:225], v[66:69]
	s_barrier
	s_add_i32 s68, s68, s30
	v_lshl_add_u64 v[142:143], s[26:27], 0, v[0:1]
	s_mov_b32 m0, s68
	ds_read_b128 v[180:183], v146 offset:16384
	ds_read_b128 v[184:187], v146 offset:17408
	ds_read_b128 v[188:191], v146 offset:18432
	ds_read_b128 v[192:195], v146 offset:19456
	ds_read_b128 v[210:213], v146 offset:20480
	ds_read_b128 v[214:217], v146 offset:21504
	ds_read_b128 v[218:221], v146 offset:22528
	ds_read_b128 v[222:225], v146 offset:23552
	global_load_lds_dwordx4 v[142:143], off
	s_add_i32 m0, s68, 0x2000
	s_add_u32 s68, s26, 0x80000
	v_lshl_add_u64 v[240:241], s[26:27], 0, v[130:131]
	s_addc_u32 s69, s27, 0
	s_add_i32 s70, s70, s30
	global_load_lds_dwordx4 v[240:241], off
	v_lshl_add_u64 v[242:243], s[68:69], 0, v[0:1]
	s_mov_b32 m0, s70
	v_lshl_add_u64 v[244:245], s[28:29], 0, v[132:133]
	global_load_lds_dwordx4 v[242:243], off
	v_lshl_add_u64 v[242:243], s[68:69], 0, v[130:131]
	s_add_i32 m0, s70, 0x2000
	s_nop 0
	global_load_lds_dwordx4 v[242:243], off
	v_lshl_add_u64 v[242:243], s[28:29], 0, v[134:135]
	s_waitcnt vmcnt(4)
	s_waitcnt lgkmcnt(0)
	s_barrier
; #define PG8_STAGE(bufoff, gbase, voff) do { _Pragma("unroll") for (int _i = 0; _i < 2; ++_i) \
;         __builtin_amdgcn_global_load_lds((const unsigned*)((const char*)(gbase) + (voff)[_i]), (LAS unsigned*)(lds + (bufoff) + ldsw + _i * 8192), 16, 0, 0); } while (0)
; #define PG8_LDA(dst, b, h) do { _Pragma("unroll") for (int m = 0; m < 4; ++m) _Pragma("unroll") for (int k = 0; k < 2; ++k) dst[m][k] = *(const LAS bf16x8*)(lds + PG8_SA(b, h) + aoff + m * 2048 + k * 1024); } while (0)
; #define PG8_LDB(dst, b, h) do { _Pragma("unroll") for (int n = 0; n < 2; ++n) _Pragma("unroll") for (int k = 0; k < 2; ++k) dst[n][k] = *(const LAS bf16x8*)(lds + PG8_SB(b, h) + boff + n * 2048 + k * 1024); } while (0)
; #define PG8_MMA(ai, bj, At, Bt) do { __builtin_amdgcn_s_setprio(1); _Pragma("unroll") for (int m = 0; m < 4; ++m) _Pragma("unroll") for (int n = 0; n < 2; ++n) _Pragma("unroll") for (int k = 0; k < 2; ++k) \
;         acc[ai][bj][m][n] = __builtin_amdgcn_mfma_f32_16x16x32_bf16(Bt[n][k], At[m][k], acc[ai][bj][m][n], 0, 0, 0); __builtin_amdgcn_s_setprio(0); } while (0)
; #define PG8_WAIT_V(n) asm volatile("s_waitcnt vmcnt(" #n ")" ::: "memory")
; #define PG8_WAIT_L(n) asm volatile("s_waitcnt lgkmcnt(" #n ")" ::: "memory")
; #define PG8_BAR __builtin_amdgcn_s_barrier()
; #define PG8_SCHED __builtin_amdgcn_sched_barrier(0)
; template <class Epi, bool ALIGN_EPI>
; __device__ __forceinline__ void gemm_phase(LAS unsigned char* lds, const int tid, const Gemm g, const StaticOrder& S, const Epi& E) {
;     ...
;             PG8_WAIT_V(8); PG8_WAIT_L(0); PG8_BAR; PG8_MMA(1, 0, At, B0); PG8_MMA(1, 1, At, B1); PG8_BAR; PG8_SCHED;
;             PG8_LDB(B0, 1, 0); PG8_LDB(B1, 1, 1); PG8_SCHED; PG8_LDA(At, 1, 0); PG8_STAGE(PG8_SA(0, 1), a2 + hstepA, voffA);
;             PG8_WAIT_V(8); PG8_WAIT_L(0); PG8_BAR; PG8_MMA(0, 0, At, B0); PG8_MMA(0, 1, At, B1); PG8_BAR; PG8_SCHED;
	v_mfma_f32_16x16x32_bf16 v[62:65], v[148:151], v[180:183], v[62:65]
	v_mfma_f32_16x16x32_bf16 v[58:61], v[156:159], v[180:183], v[58:61]
	v_mfma_f32_16x16x32_bf16 v[46:49], v[148:151], v[188:191], v[46:49]
	v_mfma_f32_16x16x32_bf16 v[42:45], v[156:159], v[188:191], v[42:45]
	v_mfma_f32_16x16x32_bf16 v[30:33], v[148:151], v[210:213], v[30:33]
	v_mfma_f32_16x16x32_bf16 v[26:29], v[156:159], v[210:213], v[26:29]
	v_mfma_f32_16x16x32_bf16 v[14:17], v[148:151], v[218:221], v[14:17]
	v_mfma_f32_16x16x32_bf16 v[10:13], v[156:159], v[218:221], v[10:13]
	v_mfma_f32_16x16x32_bf16 v[62:65], v[152:155], v[184:187], v[62:65]
	v_mfma_f32_16x16x32_bf16 v[58:61], v[160:163], v[184:187], v[58:61]
	v_mfma_f32_16x16x32_bf16 v[46:49], v[152:155], v[192:195], v[46:49]
	v_mfma_f32_16x16x32_bf16 v[42:45], v[160:163], v[192:195], v[42:45]
	v_mfma_f32_16x16x32_bf16 v[30:33], v[152:155], v[214:217], v[30:33]
	v_mfma_f32_16x16x32_bf16 v[26:29], v[160:163], v[214:217], v[26:29]
	v_mfma_f32_16x16x32_bf16 v[14:17], v[152:155], v[222:225], v[14:17]
	v_mfma_f32_16x16x32_bf16 v[10:13], v[160:163], v[222:225], v[10:13]
	v_mfma_f32_16x16x32_bf16 v[54:57], v[164:167], v[180:183], v[54:57]
	v_mfma_f32_16x16x32_bf16 v[50:53], v[172:175], v[180:183], v[50:53]
	v_mfma_f32_16x16x32_bf16 v[38:41], v[164:167], v[188:191], v[38:41]
	v_mfma_f32_16x16x32_bf16 v[34:37], v[172:175], v[188:191], v[34:37]
	v_mfma_f32_16x16x32_bf16 v[22:25], v[164:167], v[210:213], v[22:25]
	v_mfma_f32_16x16x32_bf16 v[18:21], v[172:175], v[210:213], v[18:21]
	v_mfma_f32_16x16x32_bf16 v[6:9], v[164:167], v[218:221], v[6:9]
	v_mfma_f32_16x16x32_bf16 v[2:5], v[172:175], v[218:221], v[2:5]
	v_mfma_f32_16x16x32_bf16 v[54:57], v[168:171], v[184:187], v[54:57]
	v_mfma_f32_16x16x32_bf16 v[50:53], v[176:179], v[184:187], v[50:53]
	v_mfma_f32_16x16x32_bf16 v[38:41], v[168:171], v[192:195], v[38:41]
	v_mfma_f32_16x16x32_bf16 v[34:37], v[176:179], v[192:195], v[34:37]
	v_mfma_f32_16x16x32_bf16 v[22:25], v[168:171], v[214:217], v[22:25]
	v_mfma_f32_16x16x32_bf16 v[18:21], v[176:179], v[214:217], v[18:21]
	v_mfma_f32_16x16x32_bf16 v[6:9], v[168:171], v[222:225], v[6:9]
	v_mfma_f32_16x16x32_bf16 v[2:5], v[176:179], v[222:225], v[2:5]
	s_barrier
	s_add_i32 s68, 0, 0x18000
	v_add_u32_e32 v147, s68, v145
	s_add_i32 s69, 0, 0x1c000
	ds_read_b128 v[148:151], v147
	ds_read_b128 v[152:155], v147 offset:1024
	ds_read_b128 v[156:159], v147 offset:2048
	ds_read_b128 v[160:163], v147 offset:3072
	v_add_u32_e32 v147, s69, v145
	ds_read_b128 v[164:167], v147
	ds_read_b128 v[168:171], v147 offset:1024
	ds_read_b128 v[172:175], v147 offset:2048
	ds_read_b128 v[176:179], v147 offset:3072
	s_mov_b32 m0, s23
	s_nop 0
	global_load_lds_dwordx4 v[242:243], off
	s_mov_b32 m0, s52
	s_nop 0
	global_load_lds_dwordx4 v[244:245], off
	s_add_u32 s28, s28, 0x80000
	s_addc_u32 s29, s29, 0
	s_mov_b32 m0, s54
	v_lshl_add_u64 v[246:247], s[28:29], 0, v[134:135]
	ds_read_b128 v[180:183], v146 offset:32768
	ds_read_b128 v[184:187], v146 offset:33792
	ds_read_b128 v[188:191], v146 offset:34816
	ds_read_b128 v[192:195], v146 offset:35840
	ds_read_b128 v[210:213], v146 offset:36864
	ds_read_b128 v[214:217], v146 offset:37888
	ds_read_b128 v[218:221], v146 offset:38912
	ds_read_b128 v[222:225], v146 offset:39936
	global_load_lds_dwordx4 v[246:247], off
	v_lshl_add_u64 v[246:247], s[28:29], 0, v[132:133]
	s_mov_b32 m0, s55
	s_nop 0
	global_load_lds_dwordx4 v[246:247], off
	s_nop 0
	s_waitcnt lgkmcnt(0)
	s_barrier
; #define PG8_STAGE(bufoff, gbase, voff) do { _Pragma("unroll") for (int _i = 0; _i < 2; ++_i) \
;         __builtin_amdgcn_global_load_lds((const unsigned*)((const char*)(gbase) + (voff)[_i]), (LAS unsigned*)(lds + (bufoff) + ldsw + _i * 8192), 16, 0, 0); } while (0)
; #define PG8_LDA(dst, b, h) do { _Pragma("unroll") for (int m = 0; m < 4; ++m) _Pragma("unroll") for (int k = 0; k < 2; ++k) dst[m][k] = *(const LAS bf16x8*)(lds + PG8_SA(b, h) + aoff + m * 2048 + k * 1024); } while (0)
; #define PG8_MMA(ai, bj, At, Bt) do { __builtin_amdgcn_s_setprio(1); _Pragma("unroll") for (int m = 0; m < 4; ++m) _Pragma("unroll") for (int n = 0; n < 2; ++n) _Pragma("unroll") for (int k = 0; k < 2; ++k) \
;         acc[ai][bj][m][n] = __builtin_amdgcn_mfma_f32_16x16x32_bf16(Bt[n][k], At[m][k], acc[ai][bj][m][n], 0, 0, 0); __builtin_amdgcn_s_setprio(0); } while (0)
; #define PG8_WAIT_V(n) asm volatile("s_waitcnt vmcnt(" #n ")" ::: "memory")
; #define PG8_WAIT_L(n) asm volatile("s_waitcnt lgkmcnt(" #n ")" ::: "memory")
; #define PG8_BAR __builtin_amdgcn_s_barrier()
; #define PG8_SCHED __builtin_amdgcn_sched_barrier(0)
; template <class Epi, bool ALIGN_EPI>
; __device__ __forceinline__ void gemm_phase(LAS unsigned char* lds, const int tid, const Gemm g, const StaticOrder& S, const Epi& E) {
;     ...
;             PG8_WAIT_V(8); PG8_WAIT_L(0); PG8_BAR; PG8_MMA(0, 0, At, B0); PG8_MMA(0, 1, At, B1); PG8_BAR; PG8_SCHED;
;             PG8_LDA(At, 1, 1); PG8_STAGE(PG8_SB(1, 0), b3, voffB); PG8_STAGE(PG8_SB(1, 1), b3 + hstepB, voffB); PG8_STAGE(PG8_SA(1, 0), a3, voffA);
;             PG8_WAIT_V(8); PG8_WAIT_L(0); PG8_BAR; PG8_MMA(1, 0, At, B0); PG8_MMA(1, 1, At, B1); PG8_BAR; PG8_SCHED;
;         }
;         if constexpr (ALIGN_EPI) { if (wr == 0) PG8_BAR; }
	v_mfma_f32_16x16x32_bf16 v[126:129], v[148:151], v[180:183], v[126:129]
	v_mfma_f32_16x16x32_bf16 v[122:125], v[156:159], v[180:183], v[122:125]
	v_mfma_f32_16x16x32_bf16 v[110:113], v[148:151], v[188:191], v[110:113]
	v_mfma_f32_16x16x32_bf16 v[106:109], v[156:159], v[188:191], v[106:109]
	v_mfma_f32_16x16x32_bf16 v[94:97], v[148:151], v[210:213], v[94:97]
	v_mfma_f32_16x16x32_bf16 v[90:93], v[156:159], v[210:213], v[90:93]
	v_mfma_f32_16x16x32_bf16 v[78:81], v[148:151], v[218:221], v[78:81]
	v_mfma_f32_16x16x32_bf16 v[74:77], v[156:159], v[218:221], v[74:77]
	v_mfma_f32_16x16x32_bf16 v[126:129], v[152:155], v[184:187], v[126:129]
	v_mfma_f32_16x16x32_bf16 v[122:125], v[160:163], v[184:187], v[122:125]
	v_mfma_f32_16x16x32_bf16 v[110:113], v[152:155], v[192:195], v[110:113]
	v_mfma_f32_16x16x32_bf16 v[106:109], v[160:163], v[192:195], v[106:109]
	v_mfma_f32_16x16x32_bf16 v[94:97], v[152:155], v[214:217], v[94:97]
	v_mfma_f32_16x16x32_bf16 v[90:93], v[160:163], v[214:217], v[90:93]
	v_mfma_f32_16x16x32_bf16 v[78:81], v[152:155], v[222:225], v[78:81]
	v_mfma_f32_16x16x32_bf16 v[74:77], v[160:163], v[222:225], v[74:77]
	v_mfma_f32_16x16x32_bf16 v[118:121], v[164:167], v[180:183], v[118:121]
	v_mfma_f32_16x16x32_bf16 v[114:117], v[172:175], v[180:183], v[114:117]
	v_mfma_f32_16x16x32_bf16 v[102:105], v[164:167], v[188:191], v[102:105]
	v_mfma_f32_16x16x32_bf16 v[98:101], v[172:175], v[188:191], v[98:101]
	v_mfma_f32_16x16x32_bf16 v[86:89], v[164:167], v[210:213], v[86:89]
	v_mfma_f32_16x16x32_bf16 v[82:85], v[172:175], v[210:213], v[82:85]
	v_mfma_f32_16x16x32_bf16 v[70:73], v[164:167], v[218:221], v[70:73]
	v_mfma_f32_16x16x32_bf16 v[66:69], v[172:175], v[218:221], v[66:69]
	v_mfma_f32_16x16x32_bf16 v[118:121], v[168:171], v[184:187], v[118:121]
	v_mfma_f32_16x16x32_bf16 v[114:117], v[176:179], v[184:187], v[114:117]
	v_mfma_f32_16x16x32_bf16 v[102:105], v[168:171], v[192:195], v[102:105]
	v_mfma_f32_16x16x32_bf16 v[98:101], v[176:179], v[192:195], v[98:101]
	v_mfma_f32_16x16x32_bf16 v[86:89], v[168:171], v[214:217], v[86:89]
	v_mfma_f32_16x16x32_bf16 v[82:85], v[176:179], v[214:217], v[82:85]
	v_mfma_f32_16x16x32_bf16 v[70:73], v[168:171], v[222:225], v[70:73]
	v_mfma_f32_16x16x32_bf16 v[66:69], v[176:179], v[222:225], v[66:69]
	s_barrier
	s_add_i32 s28, s68, s30
	v_lshl_add_u64 v[142:143], v[142:143], 0, s[42:43]
	s_mov_b32 m0, s28
	ds_read_b128 v[180:183], v146 offset:49152
	ds_read_b128 v[184:187], v146 offset:50176
	ds_read_b128 v[188:191], v146 offset:51200
	ds_read_b128 v[192:195], v146 offset:52224
	ds_read_b128 v[210:213], v146 offset:53248
	ds_read_b128 v[214:217], v146 offset:54272
	ds_read_b128 v[218:221], v146 offset:55296
	ds_read_b128 v[222:225], v146 offset:56320
	global_load_lds_dwordx4 v[142:143], off
	s_add_i32 m0, s28, 0x2000
	s_add_u32 s26, s26, 0x80080
	v_lshl_add_u64 v[142:143], v[240:241], 0, s[42:43]
	s_addc_u32 s27, s27, 0
	s_add_i32 s28, s69, s30
	global_load_lds_dwordx4 v[142:143], off
	v_lshl_add_u64 v[142:143], s[26:27], 0, v[0:1]
	s_mov_b32 m0, s28
	s_nop 0
	global_load_lds_dwordx4 v[142:143], off
	v_lshl_add_u64 v[142:143], s[26:27], 0, v[130:131]
	s_add_i32 m0, s28, 0x2000
	s_nop 0
	global_load_lds_dwordx4 v[142:143], off
	s_waitcnt vmcnt(4)
	s_waitcnt lgkmcnt(0)
	s_barrier
	v_mfma_f32_16x16x32_bf16 v[62:65], v[148:151], v[180:183], v[62:65]
	v_mfma_f32_16x16x32_bf16 v[58:61], v[156:159], v[180:183], v[58:61]
	v_mfma_f32_16x16x32_bf16 v[46:49], v[148:151], v[188:191], v[46:49]
	v_mfma_f32_16x16x32_bf16 v[42:45], v[156:159], v[188:191], v[42:45]
	v_mfma_f32_16x16x32_bf16 v[30:33], v[148:151], v[210:213], v[30:33]
	v_mfma_f32_16x16x32_bf16 v[26:29], v[156:159], v[210:213], v[26:29]
	v_mfma_f32_16x16x32_bf16 v[14:17], v[148:151], v[218:221], v[14:17]
	v_mfma_f32_16x16x32_bf16 v[10:13], v[156:159], v[218:221], v[10:13]
	v_mfma_f32_16x16x32_bf16 v[62:65], v[152:155], v[184:187], v[62:65]
	v_mfma_f32_16x16x32_bf16 v[58:61], v[160:163], v[184:187], v[58:61]
	v_mfma_f32_16x16x32_bf16 v[46:49], v[152:155], v[192:195], v[46:49]
	v_mfma_f32_16x16x32_bf16 v[42:45], v[160:163], v[192:195], v[42:45]
	v_mfma_f32_16x16x32_bf16 v[30:33], v[152:155], v[214:217], v[30:33]
	v_mfma_f32_16x16x32_bf16 v[26:29], v[160:163], v[214:217], v[26:29]
	v_mfma_f32_16x16x32_bf16 v[14:17], v[152:155], v[222:225], v[14:17]
	v_mfma_f32_16x16x32_bf16 v[10:13], v[160:163], v[222:225], v[10:13]
	v_mfma_f32_16x16x32_bf16 v[54:57], v[164:167], v[180:183], v[54:57]
	v_mfma_f32_16x16x32_bf16 v[50:53], v[172:175], v[180:183], v[50:53]
	v_mfma_f32_16x16x32_bf16 v[38:41], v[164:167], v[188:191], v[38:41]
	v_mfma_f32_16x16x32_bf16 v[34:37], v[172:175], v[188:191], v[34:37]
	v_mfma_f32_16x16x32_bf16 v[22:25], v[164:167], v[210:213], v[22:25]
	v_mfma_f32_16x16x32_bf16 v[18:21], v[172:175], v[210:213], v[18:21]
	v_mfma_f32_16x16x32_bf16 v[6:9], v[164:167], v[218:221], v[6:9]
	v_mfma_f32_16x16x32_bf16 v[2:5], v[172:175], v[218:221], v[2:5]
	v_mfma_f32_16x16x32_bf16 v[54:57], v[168:171], v[184:187], v[54:57]
	v_mfma_f32_16x16x32_bf16 v[50:53], v[176:179], v[184:187], v[50:53]
	v_mfma_f32_16x16x32_bf16 v[38:41], v[168:171], v[192:195], v[38:41]
	v_mfma_f32_16x16x32_bf16 v[34:37], v[176:179], v[192:195], v[34:37]
	v_mfma_f32_16x16x32_bf16 v[22:25], v[168:171], v[214:217], v[22:25]
	v_mfma_f32_16x16x32_bf16 v[18:21], v[176:179], v[214:217], v[18:21]
	v_mfma_f32_16x16x32_bf16 v[6:9], v[168:171], v[222:225], v[6:9]
	v_mfma_f32_16x16x32_bf16 v[2:5], v[176:179], v[222:225], v[2:5]
	s_barrier
	s_add_i32 s67, s67, 2
	s_add_u32 s15, s15, 0x100
	s_addc_u32 s17, s17, 0
	s_add_u32 s24, s24, 0x100
	s_addc_u32 s25, s25, 0
	s_cmp_gt_u32 s67, 29
	s_cbranch_scc0 .LBB0_143
	s_and_b64 vcc, exec, s[12:13]
	s_cbranch_vccz .LBB0_146
	s_barrier

; #define PG8_STAGE(bufoff, gbase, voff) do { _Pragma("unroll") for (int _i = 0; _i < 2; ++_i) \
;         __builtin_amdgcn_global_load_lds((const unsigned*)((const char*)(gbase) + (voff)[_i]), (LAS unsigned*)(lds + (bufoff) + ldsw + _i * 8192), 16, 0, 0); } while (0)
; #define PG8_LDA(dst, b, h) do { _Pragma("unroll") for (int m = 0; m < 4; ++m) _Pragma("unroll") for (int k = 0; k < 2; ++k) dst[m][k] = *(const LAS bf16x8*)(lds + PG8_SA(b, h) + aoff + m * 2048 + k * 1024); } while (0)
; #define PG8_LDB(dst, b, h) do { _Pragma("unroll") for (int n = 0; n < 2; ++n) _Pragma("unroll") for (int k = 0; k < 2; ++k) dst[n][k] = *(const LAS bf16x8*)(lds + PG8_SB(b, h) + boff + n * 2048 + k * 1024); } while (0)
; #define PG8_MMA(ai, bj, At, Bt) do { __builtin_amdgcn_s_setprio(1); _Pragma("unroll") for (int m = 0; m < 4; ++m) _Pragma("unroll") for (int n = 0; n < 2; ++n) _Pragma("unroll") for (int k = 0; k < 2; ++k) \
;         acc[ai][bj][m][n] = __builtin_amdgcn_mfma_f32_16x16x32_bf16(Bt[n][k], At[m][k], acc[ai][bj][m][n], 0, 0, 0); __builtin_amdgcn_s_setprio(0); } while (0)
; #define PG8_WAIT_V(n) asm volatile("s_waitcnt vmcnt(" #n ")" ::: "memory")
; #define PG8_WAIT_L(n) asm volatile("s_waitcnt lgkmcnt(" #n ")" ::: "memory")
; #define PG8_BAR __builtin_amdgcn_s_barrier()
; #define PG8_SCHED __builtin_amdgcn_sched_barrier(0)
; template <class Epi, bool ALIGN_EPI>
; __device__ __forceinline__ void gemm_phase(LAS unsigned char* lds, const int tid, const Gemm g, const StaticOrder& S, const Epi& E) {
;     ...
;             PG8_LDB(B0, 0, 0); PG8_LDB(B1, 0, 1); PG8_SCHED; PG8_LDA(At, 0, 0); PG8_STAGE(PG8_SA(1, 1), a1 + hstepA, voffA);
;             PG8_WAIT_V(8); PG8_WAIT_L(0); PG8_BAR; PG8_MMA(0, 0, At, B0); PG8_MMA(0, 1, At, B1); PG8_BAR; PG8_SCHED;
;             PG8_LDA(At, 0, 1); PG8_STAGE(PG8_SB(0, 0), b2, voffB); PG8_STAGE(PG8_SB(0, 1), b2 + hstepB, voffB); PG8_STAGE(PG8_SA(0, 0), a2, voffA);
;             PG8_WAIT_V(8); PG8_WAIT_L(0); PG8_BAR; PG8_MMA(1, 0, At, B0); PG8_MMA(1, 1, At, B1); PG8_BAR; PG8_SCHED;
.LBB0_209:
	s_add_i32 s72, s34, 2
	s_add_u32 s35, s30, 0xfff80080
	s_addc_u32 s54, s31, -1
	s_cmp_eq_u32 s21, s34
	s_cselect_b32 s55, s23, s54
	s_cselect_b32 s54, s22, s35
	s_cselect_b32 s35, s25, s71
	s_cselect_b32 s34, s24, s27
	s_add_i32 s73, 0, 0x10000
	s_add_i32 s85, 0, 0x14000
	v_add_u32_e32 v148, s73, v175
	v_add_u32_e32 v164, s85, v175
	ds_read_b128 v[136:139], v148
	ds_read_b128 v[140:143], v148 offset:1024
	ds_read_b128 v[144:147], v148 offset:2048
	ds_read_b128 v[148:151], v148 offset:3072
	ds_read_b128 v[152:155], v164
	ds_read_b128 v[156:159], v164 offset:1024
	ds_read_b128 v[160:163], v164 offset:2048
	ds_read_b128 v[164:167], v164 offset:3072
	v_lshl_add_u64 v[172:173], s[30:31], 0, v[134:135]
	s_add_i32 m0, s58, 0xc000
	ds_read_b128 v[168:171], v177
	ds_read_b128 v[178:181], v177 offset:1024
	ds_read_b128 v[182:185], v177 offset:2048
	ds_read_b128 v[186:189], v177 offset:3072
	ds_read_b128 v[190:193], v177 offset:4096
	ds_read_b128 v[210:213], v177 offset:5120
	ds_read_b128 v[214:217], v177 offset:6144
	ds_read_b128 v[218:221], v177 offset:7168
	global_load_lds_dwordx4 v[172:173], off
	v_lshl_add_u64 v[172:173], s[30:31], 0, v[132:133]
	s_add_i32 m0, s58, 0xe000
	s_nop 0
	global_load_lds_dwordx4 v[172:173], off
	s_sub_u32 s98, s30, 0x80000
	s_subb_u32 s99, s31, 0
	v_lshl_add_u64 v[172:173], s[98:99], 0, v[134:135]
	s_mov_b32 m0, s65
	s_nop 0
	global_load_lds_dwordx4 v[172:173], off
	v_lshl_add_u64 v[172:173], s[98:99], 0, v[132:133]
	s_mov_b32 m0, s66
	s_nop 0
	global_load_lds_dwordx4 v[172:173], off
	s_nop 0
	s_waitcnt lgkmcnt(0)
	s_barrier
	v_mfma_f32_16x16x32_bf16 v[126:129], v[136:139], v[168:171], v[126:129]
	v_mfma_f32_16x16x32_bf16 v[94:97], v[144:147], v[168:171], v[94:97]
	v_mfma_f32_16x16x32_bf16 v[122:125], v[136:139], v[182:185], v[122:125]
	v_mfma_f32_16x16x32_bf16 v[90:93], v[144:147], v[182:185], v[90:93]
	v_mfma_f32_16x16x32_bf16 v[118:121], v[136:139], v[190:193], v[118:121]
	v_mfma_f32_16x16x32_bf16 v[86:89], v[144:147], v[190:193], v[86:89]
	v_mfma_f32_16x16x32_bf16 v[114:117], v[136:139], v[214:217], v[114:117]
	v_mfma_f32_16x16x32_bf16 v[82:85], v[144:147], v[214:217], v[82:85]
	v_mfma_f32_16x16x32_bf16 v[126:129], v[140:143], v[178:181], v[126:129]
	v_mfma_f32_16x16x32_bf16 v[94:97], v[148:151], v[178:181], v[94:97]
	v_mfma_f32_16x16x32_bf16 v[122:125], v[140:143], v[186:189], v[122:125]
	v_mfma_f32_16x16x32_bf16 v[90:93], v[148:151], v[186:189], v[90:93]
	v_mfma_f32_16x16x32_bf16 v[118:121], v[140:143], v[210:213], v[118:121]
	v_mfma_f32_16x16x32_bf16 v[86:89], v[148:151], v[210:213], v[86:89]
	v_mfma_f32_16x16x32_bf16 v[114:117], v[140:143], v[218:221], v[114:117]
	v_mfma_f32_16x16x32_bf16 v[82:85], v[148:151], v[218:221], v[82:85]
	v_mfma_f32_16x16x32_bf16 v[62:65], v[152:155], v[168:171], v[62:65]
	v_mfma_f32_16x16x32_bf16 v[42:45], v[160:163], v[168:171], v[42:45]
	v_mfma_f32_16x16x32_bf16 v[58:61], v[152:155], v[182:185], v[58:61]
	v_mfma_f32_16x16x32_bf16 v[34:37], v[160:163], v[182:185], v[34:37]
	v_mfma_f32_16x16x32_bf16 v[54:57], v[152:155], v[190:193], v[54:57]
	v_mfma_f32_16x16x32_bf16 v[26:29], v[160:163], v[190:193], v[26:29]
	v_mfma_f32_16x16x32_bf16 v[50:53], v[152:155], v[214:217], v[50:53]
	v_mfma_f32_16x16x32_bf16 v[18:21], v[160:163], v[214:217], v[18:21]
	v_mfma_f32_16x16x32_bf16 v[62:65], v[156:159], v[178:181], v[62:65]
	v_mfma_f32_16x16x32_bf16 v[42:45], v[164:167], v[178:181], v[42:45]
	v_mfma_f32_16x16x32_bf16 v[58:61], v[156:159], v[186:189], v[58:61]
	v_mfma_f32_16x16x32_bf16 v[34:37], v[164:167], v[186:189], v[34:37]
	v_mfma_f32_16x16x32_bf16 v[54:57], v[156:159], v[210:213], v[54:57]
	v_mfma_f32_16x16x32_bf16 v[26:29], v[164:167], v[210:213], v[26:29]
	v_mfma_f32_16x16x32_bf16 v[50:53], v[156:159], v[218:221], v[50:53]
	v_mfma_f32_16x16x32_bf16 v[18:21], v[164:167], v[218:221], v[18:21]
	s_barrier
	s_add_i32 s73, s73, s56
	v_lshl_add_u64 v[172:173], s[34:35], 0, v[0:1]
	s_mov_b32 m0, s73
	ds_read_b128 v[168:171], v177 offset:16384
	ds_read_b128 v[178:181], v177 offset:17408
	ds_read_b128 v[182:185], v177 offset:18432
	ds_read_b128 v[186:189], v177 offset:19456
	ds_read_b128 v[190:193], v177 offset:20480
	ds_read_b128 v[210:213], v177 offset:21504
	ds_read_b128 v[214:217], v177 offset:22528
	ds_read_b128 v[218:221], v177 offset:23552
	global_load_lds_dwordx4 v[172:173], off
	s_add_i32 m0, s73, 0x2000
	s_add_u32 s90, s34, 0x80000
	v_lshl_add_u64 v[194:195], s[34:35], 0, v[130:131]
	s_addc_u32 s91, s35, 0
	s_add_i32 s73, s85, s56
	global_load_lds_dwordx4 v[194:195], off
	v_lshl_add_u64 v[222:223], s[90:91], 0, v[0:1]
	s_mov_b32 m0, s73
	v_lshl_add_u64 v[224:225], s[54:55], 0, v[130:131]
	global_load_lds_dwordx4 v[222:223], off
	v_lshl_add_u64 v[222:223], s[90:91], 0, v[130:131]
	s_add_i32 m0, s73, 0x2000
	s_nop 0
	global_load_lds_dwordx4 v[222:223], off
	v_lshl_add_u64 v[222:223], s[54:55], 0, v[0:1]
	s_waitcnt vmcnt(4)
	s_waitcnt lgkmcnt(0)
	s_barrier
; #define PG8_STAGE(bufoff, gbase, voff) do { _Pragma("unroll") for (int _i = 0; _i < 2; ++_i) \
;         __builtin_amdgcn_global_load_lds((const unsigned*)((const char*)(gbase) + (voff)[_i]), (LAS unsigned*)(lds + (bufoff) + ldsw + _i * 8192), 16, 0, 0); } while (0)
; #define PG8_LDA(dst, b, h) do { _Pragma("unroll") for (int m = 0; m < 4; ++m) _Pragma("unroll") for (int k = 0; k < 2; ++k) dst[m][k] = *(const LAS bf16x8*)(lds + PG8_SA(b, h) + aoff + m * 2048 + k * 1024); } while (0)
; #define PG8_LDB(dst, b, h) do { _Pragma("unroll") for (int n = 0; n < 2; ++n) _Pragma("unroll") for (int k = 0; k < 2; ++k) dst[n][k] = *(const LAS bf16x8*)(lds + PG8_SB(b, h) + boff + n * 2048 + k * 1024); } while (0)
; #define PG8_MMA(ai, bj, At, Bt) do { __builtin_amdgcn_s_setprio(1); _Pragma("unroll") for (int m = 0; m < 4; ++m) _Pragma("unroll") for (int n = 0; n < 2; ++n) _Pragma("unroll") for (int k = 0; k < 2; ++k) \
;         acc[ai][bj][m][n] = __builtin_amdgcn_mfma_f32_16x16x32_bf16(Bt[n][k], At[m][k], acc[ai][bj][m][n], 0, 0, 0); __builtin_amdgcn_s_setprio(0); } while (0)
; #define PG8_WAIT_V(n) asm volatile("s_waitcnt vmcnt(" #n ")" ::: "memory")
; #define PG8_WAIT_L(n) asm volatile("s_waitcnt lgkmcnt(" #n ")" ::: "memory")
; #define PG8_BAR __builtin_amdgcn_s_barrier()
; #define PG8_SCHED __builtin_amdgcn_sched_barrier(0)
; template <class Epi, bool ALIGN_EPI>
; __device__ __forceinline__ void gemm_phase(LAS unsigned char* lds, const int tid, const Gemm g, const StaticOrder& S, const Epi& E) {
;     ...
;             PG8_WAIT_V(8); PG8_WAIT_L(0); PG8_BAR; PG8_MMA(1, 0, At, B0); PG8_MMA(1, 1, At, B1); PG8_BAR; PG8_SCHED;
;             PG8_LDB(B0, 1, 0); PG8_LDB(B1, 1, 1); PG8_SCHED; PG8_LDA(At, 1, 0); PG8_STAGE(PG8_SA(0, 1), a2 + hstepA, voffA);
;             PG8_WAIT_V(8); PG8_WAIT_L(0); PG8_BAR; PG8_MMA(0, 0, At, B0); PG8_MMA(0, 1, At, B1); PG8_BAR; PG8_SCHED;
	v_mfma_f32_16x16x32_bf16 v[110:113], v[136:139], v[168:171], v[110:113]
	v_mfma_f32_16x16x32_bf16 v[78:81], v[144:147], v[168:171], v[78:81]
	v_mfma_f32_16x16x32_bf16 v[106:109], v[136:139], v[182:185], v[106:109]
	v_mfma_f32_16x16x32_bf16 v[74:77], v[144:147], v[182:185], v[74:77]
	v_mfma_f32_16x16x32_bf16 v[102:105], v[136:139], v[190:193], v[102:105]
	v_mfma_f32_16x16x32_bf16 v[70:73], v[144:147], v[190:193], v[70:73]
	v_mfma_f32_16x16x32_bf16 v[98:101], v[136:139], v[214:217], v[98:101]
	v_mfma_f32_16x16x32_bf16 v[66:69], v[144:147], v[214:217], v[66:69]
	v_mfma_f32_16x16x32_bf16 v[110:113], v[140:143], v[178:181], v[110:113]
	v_mfma_f32_16x16x32_bf16 v[78:81], v[148:151], v[178:181], v[78:81]
	v_mfma_f32_16x16x32_bf16 v[106:109], v[140:143], v[186:189], v[106:109]
	v_mfma_f32_16x16x32_bf16 v[74:77], v[148:151], v[186:189], v[74:77]
	v_mfma_f32_16x16x32_bf16 v[102:105], v[140:143], v[210:213], v[102:105]
	v_mfma_f32_16x16x32_bf16 v[70:73], v[148:151], v[210:213], v[70:73]
	v_mfma_f32_16x16x32_bf16 v[98:101], v[140:143], v[218:221], v[98:101]
	v_mfma_f32_16x16x32_bf16 v[66:69], v[148:151], v[218:221], v[66:69]
	v_mfma_f32_16x16x32_bf16 v[46:49], v[152:155], v[168:171], v[46:49]
	v_mfma_f32_16x16x32_bf16 v[14:17], v[160:163], v[168:171], v[14:17]
	v_mfma_f32_16x16x32_bf16 v[38:41], v[152:155], v[182:185], v[38:41]
	v_mfma_f32_16x16x32_bf16 v[10:13], v[160:163], v[182:185], v[10:13]
	v_mfma_f32_16x16x32_bf16 v[30:33], v[152:155], v[190:193], v[30:33]
	v_mfma_f32_16x16x32_bf16 v[6:9], v[160:163], v[190:193], v[6:9]
	v_mfma_f32_16x16x32_bf16 v[22:25], v[152:155], v[214:217], v[22:25]
	v_mfma_f32_16x16x32_bf16 v[2:5], v[160:163], v[214:217], v[2:5]
	v_mfma_f32_16x16x32_bf16 v[46:49], v[156:159], v[178:181], v[46:49]
	v_mfma_f32_16x16x32_bf16 v[14:17], v[164:167], v[178:181], v[14:17]
	v_mfma_f32_16x16x32_bf16 v[38:41], v[156:159], v[186:189], v[38:41]
	v_mfma_f32_16x16x32_bf16 v[10:13], v[164:167], v[186:189], v[10:13]
	v_mfma_f32_16x16x32_bf16 v[30:33], v[156:159], v[210:213], v[30:33]
	v_mfma_f32_16x16x32_bf16 v[6:9], v[164:167], v[210:213], v[6:9]
	v_mfma_f32_16x16x32_bf16 v[22:25], v[156:159], v[218:221], v[22:25]
	v_mfma_f32_16x16x32_bf16 v[2:5], v[164:167], v[218:221], v[2:5]
	s_barrier
	s_add_i32 s73, 0, 0x18000
	s_add_i32 s85, 0, 0x1c000
	v_add_u32_e32 v148, s73, v175
	v_add_u32_e32 v164, s85, v175
	ds_read_b128 v[136:139], v148
	ds_read_b128 v[140:143], v148 offset:1024
	ds_read_b128 v[144:147], v148 offset:2048
	ds_read_b128 v[148:151], v148 offset:3072
	ds_read_b128 v[152:155], v164
	ds_read_b128 v[156:159], v164 offset:1024
	ds_read_b128 v[160:163], v164 offset:2048
	ds_read_b128 v[164:167], v164 offset:3072
	s_mov_b32 m0, s58
	s_nop 0
	global_load_lds_dwordx4 v[222:223], off
	s_mov_b32 m0, s60
	s_nop 0
	global_load_lds_dwordx4 v[224:225], off
	s_add_u32 s54, s54, 0x80000
	s_addc_u32 s55, s55, 0
	s_mov_b32 m0, s61
	v_lshl_add_u64 v[240:241], s[54:55], 0, v[0:1]
	ds_read_b128 v[168:171], v177 offset:32768
	ds_read_b128 v[178:181], v177 offset:33792
	ds_read_b128 v[182:185], v177 offset:34816
	ds_read_b128 v[186:189], v177 offset:35840
	ds_read_b128 v[190:193], v177 offset:36864
	ds_read_b128 v[210:213], v177 offset:37888
	ds_read_b128 v[214:217], v177 offset:38912
	ds_read_b128 v[218:221], v177 offset:39936
	global_load_lds_dwordx4 v[240:241], off
	v_lshl_add_u64 v[240:241], s[54:55], 0, v[130:131]
	s_mov_b32 m0, s62
	s_nop 0
	global_load_lds_dwordx4 v[240:241], off
	s_nop 0
	s_waitcnt lgkmcnt(0)
	s_barrier
; #define PG8_STAGE(bufoff, gbase, voff) do { _Pragma("unroll") for (int _i = 0; _i < 2; ++_i) \
;         __builtin_amdgcn_global_load_lds((const unsigned*)((const char*)(gbase) + (voff)[_i]), (LAS unsigned*)(lds + (bufoff) + ldsw + _i * 8192), 16, 0, 0); } while (0)
; #define PG8_LDA(dst, b, h) do { _Pragma("unroll") for (int m = 0; m < 4; ++m) _Pragma("unroll") for (int k = 0; k < 2; ++k) dst[m][k] = *(const LAS bf16x8*)(lds + PG8_SA(b, h) + aoff + m * 2048 + k * 1024); } while (0)
; #define PG8_MMA(ai, bj, At, Bt) do { __builtin_amdgcn_s_setprio(1); _Pragma("unroll") for (int m = 0; m < 4; ++m) _Pragma("unroll") for (int n = 0; n < 2; ++n) _Pragma("unroll") for (int k = 0; k < 2; ++k) \
;         acc[ai][bj][m][n] = __builtin_amdgcn_mfma_f32_16x16x32_bf16(Bt[n][k], At[m][k], acc[ai][bj][m][n], 0, 0, 0); __builtin_amdgcn_s_setprio(0); } while (0)
; #define PG8_WAIT_V(n) asm volatile("s_waitcnt vmcnt(" #n ")" ::: "memory")
; #define PG8_WAIT_L(n) asm volatile("s_waitcnt lgkmcnt(" #n ")" ::: "memory")
; #define PG8_BAR __builtin_amdgcn_s_barrier()
; #define PG8_SCHED __builtin_amdgcn_sched_barrier(0)
; template <class Epi, bool ALIGN_EPI>
; __device__ __forceinline__ void gemm_phase(LAS unsigned char* lds, const int tid, const Gemm g, const StaticOrder& S, const Epi& E) {
;     ...
;             PG8_WAIT_V(8); PG8_WAIT_L(0); PG8_BAR; PG8_MMA(0, 0, At, B0); PG8_MMA(0, 1, At, B1); PG8_BAR; PG8_SCHED;
;             PG8_LDA(At, 1, 1); PG8_STAGE(PG8_SB(1, 0), b3, voffB); PG8_STAGE(PG8_SB(1, 1), b3 + hstepB, voffB); PG8_STAGE(PG8_SA(1, 0), a3, voffA);
;             PG8_WAIT_V(8); PG8_WAIT_L(0); PG8_BAR; PG8_MMA(1, 0, At, B0); PG8_MMA(1, 1, At, B1); PG8_BAR; PG8_SCHED;
;         }
;         if constexpr (ALIGN_EPI) { if (wr == 0) PG8_BAR; }
	v_mfma_f32_16x16x32_bf16 v[126:129], v[136:139], v[168:171], v[126:129]
	v_mfma_f32_16x16x32_bf16 v[94:97], v[144:147], v[168:171], v[94:97]
	v_mfma_f32_16x16x32_bf16 v[122:125], v[136:139], v[182:185], v[122:125]
	v_mfma_f32_16x16x32_bf16 v[90:93], v[144:147], v[182:185], v[90:93]
	v_mfma_f32_16x16x32_bf16 v[118:121], v[136:139], v[190:193], v[118:121]
	v_mfma_f32_16x16x32_bf16 v[86:89], v[144:147], v[190:193], v[86:89]
	v_mfma_f32_16x16x32_bf16 v[114:117], v[136:139], v[214:217], v[114:117]
	v_mfma_f32_16x16x32_bf16 v[82:85], v[144:147], v[214:217], v[82:85]
	v_mfma_f32_16x16x32_bf16 v[126:129], v[140:143], v[178:181], v[126:129]
	v_mfma_f32_16x16x32_bf16 v[94:97], v[148:151], v[178:181], v[94:97]
	v_mfma_f32_16x16x32_bf16 v[122:125], v[140:143], v[186:189], v[122:125]
	v_mfma_f32_16x16x32_bf16 v[90:93], v[148:151], v[186:189], v[90:93]
	v_mfma_f32_16x16x32_bf16 v[118:121], v[140:143], v[210:213], v[118:121]
	v_mfma_f32_16x16x32_bf16 v[86:89], v[148:151], v[210:213], v[86:89]
	v_mfma_f32_16x16x32_bf16 v[114:117], v[140:143], v[218:221], v[114:117]
	v_mfma_f32_16x16x32_bf16 v[82:85], v[148:151], v[218:221], v[82:85]
	v_mfma_f32_16x16x32_bf16 v[62:65], v[152:155], v[168:171], v[62:65]
	v_mfma_f32_16x16x32_bf16 v[42:45], v[160:163], v[168:171], v[42:45]
	v_mfma_f32_16x16x32_bf16 v[58:61], v[152:155], v[182:185], v[58:61]
	v_mfma_f32_16x16x32_bf16 v[34:37], v[160:163], v[182:185], v[34:37]
	v_mfma_f32_16x16x32_bf16 v[54:57], v[152:155], v[190:193], v[54:57]
	v_mfma_f32_16x16x32_bf16 v[26:29], v[160:163], v[190:193], v[26:29]
	v_mfma_f32_16x16x32_bf16 v[50:53], v[152:155], v[214:217], v[50:53]
	v_mfma_f32_16x16x32_bf16 v[18:21], v[160:163], v[214:217], v[18:21]
	v_mfma_f32_16x16x32_bf16 v[62:65], v[156:159], v[178:181], v[62:65]
	v_mfma_f32_16x16x32_bf16 v[42:45], v[164:167], v[178:181], v[42:45]
	v_mfma_f32_16x16x32_bf16 v[58:61], v[156:159], v[186:189], v[58:61]
	v_mfma_f32_16x16x32_bf16 v[34:37], v[164:167], v[186:189], v[34:37]
	v_mfma_f32_16x16x32_bf16 v[54:57], v[156:159], v[210:213], v[54:57]
	v_mfma_f32_16x16x32_bf16 v[26:29], v[164:167], v[210:213], v[26:29]
	v_mfma_f32_16x16x32_bf16 v[50:53], v[156:159], v[218:221], v[50:53]
	v_mfma_f32_16x16x32_bf16 v[18:21], v[164:167], v[218:221], v[18:21]
	s_barrier
	s_add_i32 s54, s73, s56
	v_lshl_add_u64 v[172:173], v[172:173], 0, s[42:43]
	s_mov_b32 m0, s54
	ds_read_b128 v[168:171], v177 offset:49152
	ds_read_b128 v[178:181], v177 offset:50176
	ds_read_b128 v[182:185], v177 offset:51200
	ds_read_b128 v[186:189], v177 offset:52224
	ds_read_b128 v[190:193], v177 offset:53248
	ds_read_b128 v[210:213], v177 offset:54272
	ds_read_b128 v[214:217], v177 offset:55296
	ds_read_b128 v[218:221], v177 offset:56320
	global_load_lds_dwordx4 v[172:173], off
	s_add_i32 m0, s54, 0x2000
	s_add_u32 s34, s34, 0x80080
	v_lshl_add_u64 v[172:173], v[194:195], 0, s[42:43]
	s_addc_u32 s35, s35, 0
	s_add_i32 s54, s85, s56
	global_load_lds_dwordx4 v[172:173], off
	v_lshl_add_u64 v[172:173], s[34:35], 0, v[0:1]
	s_mov_b32 m0, s54
	s_nop 0
	global_load_lds_dwordx4 v[172:173], off
	v_lshl_add_u64 v[172:173], s[34:35], 0, v[130:131]
	s_add_i32 m0, s54, 0x2000
	s_nop 0
	global_load_lds_dwordx4 v[172:173], off
	s_waitcnt vmcnt(4)
	s_waitcnt lgkmcnt(0)
	s_barrier
	v_mfma_f32_16x16x32_bf16 v[110:113], v[136:139], v[168:171], v[110:113]
	v_mfma_f32_16x16x32_bf16 v[78:81], v[144:147], v[168:171], v[78:81]
	v_mfma_f32_16x16x32_bf16 v[106:109], v[136:139], v[182:185], v[106:109]
	v_mfma_f32_16x16x32_bf16 v[74:77], v[144:147], v[182:185], v[74:77]
	v_mfma_f32_16x16x32_bf16 v[102:105], v[136:139], v[190:193], v[102:105]
	v_mfma_f32_16x16x32_bf16 v[70:73], v[144:147], v[190:193], v[70:73]
	v_mfma_f32_16x16x32_bf16 v[98:101], v[136:139], v[214:217], v[98:101]
	v_mfma_f32_16x16x32_bf16 v[66:69], v[144:147], v[214:217], v[66:69]
	v_mfma_f32_16x16x32_bf16 v[110:113], v[140:143], v[178:181], v[110:113]
	v_mfma_f32_16x16x32_bf16 v[78:81], v[148:151], v[178:181], v[78:81]
	v_mfma_f32_16x16x32_bf16 v[106:109], v[140:143], v[186:189], v[106:109]
	v_mfma_f32_16x16x32_bf16 v[74:77], v[148:151], v[186:189], v[74:77]
	v_mfma_f32_16x16x32_bf16 v[102:105], v[140:143], v[210:213], v[102:105]
	v_mfma_f32_16x16x32_bf16 v[70:73], v[148:151], v[210:213], v[70:73]
	v_mfma_f32_16x16x32_bf16 v[98:101], v[140:143], v[218:221], v[98:101]
	v_mfma_f32_16x16x32_bf16 v[66:69], v[148:151], v[218:221], v[66:69]
	v_mfma_f32_16x16x32_bf16 v[46:49], v[152:155], v[168:171], v[46:49]
	v_mfma_f32_16x16x32_bf16 v[14:17], v[160:163], v[168:171], v[14:17]
	v_mfma_f32_16x16x32_bf16 v[38:41], v[152:155], v[182:185], v[38:41]
	v_mfma_f32_16x16x32_bf16 v[10:13], v[160:163], v[182:185], v[10:13]
	v_mfma_f32_16x16x32_bf16 v[30:33], v[152:155], v[190:193], v[30:33]
	v_mfma_f32_16x16x32_bf16 v[6:9], v[160:163], v[190:193], v[6:9]
	v_mfma_f32_16x16x32_bf16 v[22:25], v[152:155], v[214:217], v[22:25]
	v_mfma_f32_16x16x32_bf16 v[2:5], v[160:163], v[214:217], v[2:5]
	v_mfma_f32_16x16x32_bf16 v[46:49], v[156:159], v[178:181], v[46:49]
	v_mfma_f32_16x16x32_bf16 v[14:17], v[164:167], v[178:181], v[14:17]
	v_mfma_f32_16x16x32_bf16 v[38:41], v[156:159], v[186:189], v[38:41]
	v_mfma_f32_16x16x32_bf16 v[10:13], v[164:167], v[186:189], v[10:13]
	v_mfma_f32_16x16x32_bf16 v[30:33], v[156:159], v[210:213], v[30:33]
	v_mfma_f32_16x16x32_bf16 v[6:9], v[164:167], v[210:213], v[6:9]
	v_mfma_f32_16x16x32_bf16 v[22:25], v[156:159], v[218:221], v[22:25]
	v_mfma_f32_16x16x32_bf16 v[2:5], v[164:167], v[218:221], v[2:5]
	s_barrier
	s_add_u32 s27, s27, 0x100
	s_addc_u32 s71, s71, 0
	s_add_u32 s30, s30, 0x100
	s_addc_u32 s31, s31, 0
	s_cmp_ge_u32 s72, s19
	s_mov_b32 s34, s72
	s_cbranch_scc0 .LBB0_209
	s_and_b64 vcc, exec, s[16:17]
	s_cbranch_vccz .LBB0_212
	s_barrier

; #define PG8_STAGE(bufoff, gbase, voff) do { _Pragma("unroll") for (int _i = 0; _i < 2; ++_i) \
;         __builtin_amdgcn_global_load_lds((const unsigned*)((const char*)(gbase) + (voff)[_i]), (LAS unsigned*)(lds + (bufoff) + ldsw + _i * 8192), 16, 0, 0); } while (0)
; #define PG8_LDA(dst, b, h) do { _Pragma("unroll") for (int m = 0; m < 4; ++m) _Pragma("unroll") for (int k = 0; k < 2; ++k) dst[m][k] = *(const LAS bf16x8*)(lds + PG8_SA(b, h) + aoff + m * 2048 + k * 1024); } while (0)
; #define PG8_LDB(dst, b, h) do { _Pragma("unroll") for (int n = 0; n < 2; ++n) _Pragma("unroll") for (int k = 0; k < 2; ++k) dst[n][k] = *(const LAS bf16x8*)(lds + PG8_SB(b, h) + boff + n * 2048 + k * 1024); } while (0)
; #define PG8_MMA(ai, bj, At, Bt) do { __builtin_amdgcn_s_setprio(1); _Pragma("unroll") for (int m = 0; m < 4; ++m) _Pragma("unroll") for (int n = 0; n < 2; ++n) _Pragma("unroll") for (int k = 0; k < 2; ++k) \
;         acc[ai][bj][m][n] = __builtin_amdgcn_mfma_f32_16x16x32_bf16(Bt[n][k], At[m][k], acc[ai][bj][m][n], 0, 0, 0); __builtin_amdgcn_s_setprio(0); } while (0)
; #define PG8_WAIT_V(n) asm volatile("s_waitcnt vmcnt(" #n ")" ::: "memory")
; #define PG8_WAIT_L(n) asm volatile("s_waitcnt lgkmcnt(" #n ")" ::: "memory")
; #define PG8_BAR __builtin_amdgcn_s_barrier()
; #define PG8_SCHED __builtin_amdgcn_sched_barrier(0)
; template <class Epi, bool ALIGN_EPI>
; __device__ __forceinline__ void gemm_phase(LAS unsigned char* lds, const int tid, const Gemm g, const StaticOrder& S, const Epi& E) {
;     ...
;             PG8_LDB(B0, 0, 0); PG8_LDB(B1, 0, 1); PG8_SCHED; PG8_LDA(At, 0, 0); PG8_STAGE(PG8_SA(1, 1), a1 + hstepA, voffA);
;             PG8_WAIT_V(8); PG8_WAIT_L(0); PG8_BAR; PG8_MMA(0, 0, At, B0); PG8_MMA(0, 1, At, B1); PG8_BAR; PG8_SCHED;
;             PG8_LDA(At, 0, 1); PG8_STAGE(PG8_SB(0, 0), b2, voffB); PG8_STAGE(PG8_SB(0, 1), b2 + hstepB, voffB); PG8_STAGE(PG8_SA(0, 0), a2, voffA);
;             PG8_WAIT_V(8); PG8_WAIT_L(0); PG8_BAR; PG8_MMA(1, 0, At, B0); PG8_MMA(1, 1, At, B1); PG8_BAR; PG8_SCHED;
.LBB0_263:
	s_add_i32 s5, s5, 2
	s_add_u32 s34, s30, 0xfff80080
	s_addc_u32 s35, s31, -1
	s_add_i32 s94, 0, 0x10000
	s_cmp_eq_u32 s91, s92
	s_cselect_b32 s55, s23, s35
	s_cselect_b32 s54, s22, s34
	v_add_u32_e32 v0, s94, v205
	s_cselect_b32 s35, s25, s36
	s_cselect_b32 s34, s24, s21
	s_add_i32 s96, 0, 0x14000
	ds_read_b128 v[132:135], v0
	ds_read_b128 v[136:139], v0 offset:1024
	ds_read_b128 v[140:143], v0 offset:2048
	ds_read_b128 v[144:147], v0 offset:3072
	v_add_u32_e32 v0, s96, v205
	ds_read_b128 v[148:151], v0
	ds_read_b128 v[152:155], v0 offset:1024
	ds_read_b128 v[156:159], v0 offset:2048
	ds_read_b128 v[160:163], v0 offset:3072
	v_lshl_add_u64 v[2:3], s[30:31], 0, v[220:221]
	s_add_i32 m0, s68, 0xc000
	ds_read_b128 v[164:167], v209
	ds_read_b128 v[168:171], v209 offset:1024
	ds_read_b128 v[172:175], v209 offset:2048
	ds_read_b128 v[176:179], v209 offset:3072
	ds_read_b128 v[180:183], v209 offset:4096
	ds_read_b128 v[184:187], v209 offset:5120
	ds_read_b128 v[188:191], v209 offset:6144
	ds_read_b128 v[192:195], v209 offset:7168
	global_load_lds_dwordx4 v[2:3], off
	v_lshl_add_u64 v[2:3], s[30:31], 0, v[218:219]
	s_add_i32 m0, s68, 0xe000
	s_nop 0
	global_load_lds_dwordx4 v[2:3], off
	s_sub_u32 s98, s30, 0x80000
	s_subb_u32 s99, s31, 0
	v_lshl_add_u64 v[2:3], s[98:99], 0, v[220:221]
	s_mov_b32 m0, s72
	s_nop 0
	global_load_lds_dwordx4 v[2:3], off
	v_lshl_add_u64 v[2:3], s[98:99], 0, v[218:219]
	s_mov_b32 m0, s73
	s_nop 0
	global_load_lds_dwordx4 v[2:3], off
	s_nop 0
	s_waitcnt lgkmcnt(0)
	s_barrier
	v_mfma_f32_16x16x32_bf16 v[128:131], v[132:135], v[164:167], v[128:131]
	v_mfma_f32_16x16x32_bf16 v[124:127], v[140:143], v[164:167], v[124:127]
	v_mfma_f32_16x16x32_bf16 v[112:115], v[132:135], v[172:175], v[112:115]
	v_mfma_f32_16x16x32_bf16 v[108:111], v[140:143], v[172:175], v[108:111]
	v_mfma_f32_16x16x32_bf16 v[96:99], v[132:135], v[180:183], v[96:99]
	v_mfma_f32_16x16x32_bf16 v[92:95], v[140:143], v[180:183], v[92:95]
	v_mfma_f32_16x16x32_bf16 v[80:83], v[132:135], v[188:191], v[80:83]
	v_mfma_f32_16x16x32_bf16 v[76:79], v[140:143], v[188:191], v[76:79]
	v_mfma_f32_16x16x32_bf16 v[128:131], v[136:139], v[168:171], v[128:131]
	v_mfma_f32_16x16x32_bf16 v[124:127], v[144:147], v[168:171], v[124:127]
	v_mfma_f32_16x16x32_bf16 v[112:115], v[136:139], v[176:179], v[112:115]
	v_mfma_f32_16x16x32_bf16 v[108:111], v[144:147], v[176:179], v[108:111]
	v_mfma_f32_16x16x32_bf16 v[96:99], v[136:139], v[184:187], v[96:99]
	v_mfma_f32_16x16x32_bf16 v[92:95], v[144:147], v[184:187], v[92:95]
	v_mfma_f32_16x16x32_bf16 v[80:83], v[136:139], v[192:195], v[80:83]
	v_mfma_f32_16x16x32_bf16 v[76:79], v[144:147], v[192:195], v[76:79]
	v_mfma_f32_16x16x32_bf16 v[120:123], v[148:151], v[164:167], v[120:123]
	v_mfma_f32_16x16x32_bf16 v[116:119], v[156:159], v[164:167], v[116:119]
	v_mfma_f32_16x16x32_bf16 v[104:107], v[148:151], v[172:175], v[104:107]
	v_mfma_f32_16x16x32_bf16 v[100:103], v[156:159], v[172:175], v[100:103]
	v_mfma_f32_16x16x32_bf16 v[88:91], v[148:151], v[180:183], v[88:91]
	v_mfma_f32_16x16x32_bf16 v[84:87], v[156:159], v[180:183], v[84:87]
	v_mfma_f32_16x16x32_bf16 v[72:75], v[148:151], v[188:191], v[72:75]
	v_mfma_f32_16x16x32_bf16 v[68:71], v[156:159], v[188:191], v[68:71]
	v_mfma_f32_16x16x32_bf16 v[120:123], v[152:155], v[168:171], v[120:123]
	v_mfma_f32_16x16x32_bf16 v[116:119], v[160:163], v[168:171], v[116:119]
	v_mfma_f32_16x16x32_bf16 v[104:107], v[152:155], v[176:179], v[104:107]
	v_mfma_f32_16x16x32_bf16 v[100:103], v[160:163], v[176:179], v[100:103]
	v_mfma_f32_16x16x32_bf16 v[88:91], v[152:155], v[184:187], v[88:91]
	v_mfma_f32_16x16x32_bf16 v[84:87], v[160:163], v[184:187], v[84:87]
	v_mfma_f32_16x16x32_bf16 v[72:75], v[152:155], v[192:195], v[72:75]
	v_mfma_f32_16x16x32_bf16 v[68:71], v[160:163], v[192:195], v[68:71]
	s_barrier
	s_add_i32 s94, s94, s67
	v_lshl_add_u64 v[240:241], s[34:35], 0, v[212:213]
	s_mov_b32 m0, s94
	ds_read_b128 v[164:167], v209 offset:16384
	ds_read_b128 v[168:171], v209 offset:17408
	ds_read_b128 v[172:175], v209 offset:18432
	ds_read_b128 v[176:179], v209 offset:19456
	ds_read_b128 v[180:183], v209 offset:20480
	ds_read_b128 v[184:187], v209 offset:21504
	ds_read_b128 v[188:191], v209 offset:22528
	ds_read_b128 v[192:195], v209 offset:23552
	global_load_lds_dwordx4 v[240:241], off
	s_add_i32 m0, s94, 0x2000
	s_add_u32 s94, s34, 0x80000
	v_lshl_add_u64 v[242:243], s[34:35], 0, v[216:217]
	s_addc_u32 s95, s35, 0
	s_add_i32 s96, s96, s67
	global_load_lds_dwordx4 v[242:243], off
	v_lshl_add_u64 v[2:3], s[94:95], 0, v[212:213]
	s_mov_b32 m0, s96
	v_lshl_add_u64 v[244:245], s[54:55], 0, v[210:211]
	global_load_lds_dwordx4 v[2:3], off
	v_lshl_add_u64 v[2:3], s[94:95], 0, v[216:217]
	s_add_i32 m0, s96, 0x2000
	v_lshl_add_u64 v[246:247], s[54:55], 0, v[214:215]
	global_load_lds_dwordx4 v[2:3], off
	s_waitcnt vmcnt(4)
	s_waitcnt lgkmcnt(0)
	s_barrier
; #define PG8_STAGE(bufoff, gbase, voff) do { _Pragma("unroll") for (int _i = 0; _i < 2; ++_i) \
;         __builtin_amdgcn_global_load_lds((const unsigned*)((const char*)(gbase) + (voff)[_i]), (LAS unsigned*)(lds + (bufoff) + ldsw + _i * 8192), 16, 0, 0); } while (0)
; #define PG8_LDA(dst, b, h) do { _Pragma("unroll") for (int m = 0; m < 4; ++m) _Pragma("unroll") for (int k = 0; k < 2; ++k) dst[m][k] = *(const LAS bf16x8*)(lds + PG8_SA(b, h) + aoff + m * 2048 + k * 1024); } while (0)
; #define PG8_LDB(dst, b, h) do { _Pragma("unroll") for (int n = 0; n < 2; ++n) _Pragma("unroll") for (int k = 0; k < 2; ++k) dst[n][k] = *(const LAS bf16x8*)(lds + PG8_SB(b, h) + boff + n * 2048 + k * 1024); } while (0)
; #define PG8_MMA(ai, bj, At, Bt) do { __builtin_amdgcn_s_setprio(1); _Pragma("unroll") for (int m = 0; m < 4; ++m) _Pragma("unroll") for (int n = 0; n < 2; ++n) _Pragma("unroll") for (int k = 0; k < 2; ++k) \
;         acc[ai][bj][m][n] = __builtin_amdgcn_mfma_f32_16x16x32_bf16(Bt[n][k], At[m][k], acc[ai][bj][m][n], 0, 0, 0); __builtin_amdgcn_s_setprio(0); } while (0)
; #define PG8_WAIT_V(n) asm volatile("s_waitcnt vmcnt(" #n ")" ::: "memory")
; #define PG8_WAIT_L(n) asm volatile("s_waitcnt lgkmcnt(" #n ")" ::: "memory")
; #define PG8_BAR __builtin_amdgcn_s_barrier()
; #define PG8_SCHED __builtin_amdgcn_sched_barrier(0)
; template <class Epi, bool ALIGN_EPI>
; __device__ __forceinline__ void gemm_phase(LAS unsigned char* lds, const int tid, const Gemm g, const StaticOrder& S, const Epi& E) {
;     ...
;             PG8_WAIT_V(8); PG8_WAIT_L(0); PG8_BAR; PG8_MMA(1, 0, At, B0); PG8_MMA(1, 1, At, B1); PG8_BAR; PG8_SCHED;
;             PG8_LDB(B0, 1, 0); PG8_LDB(B1, 1, 1); PG8_SCHED; PG8_LDA(At, 1, 0); PG8_STAGE(PG8_SA(0, 1), a2 + hstepA, voffA);
;             PG8_WAIT_V(8); PG8_WAIT_L(0); PG8_BAR; PG8_MMA(0, 0, At, B0); PG8_MMA(0, 1, At, B1); PG8_BAR; PG8_SCHED;
	v_mfma_f32_16x16x32_bf16 v[64:67], v[132:135], v[164:167], v[64:67]
	v_mfma_f32_16x16x32_bf16 v[60:63], v[140:143], v[164:167], v[60:63]
	v_mfma_f32_16x16x32_bf16 v[48:51], v[132:135], v[172:175], v[48:51]
	v_mfma_f32_16x16x32_bf16 v[44:47], v[140:143], v[172:175], v[44:47]
	v_mfma_f32_16x16x32_bf16 v[32:35], v[132:135], v[180:183], v[32:35]
	v_mfma_f32_16x16x32_bf16 v[28:31], v[140:143], v[180:183], v[28:31]
	v_mfma_f32_16x16x32_bf16 v[16:19], v[132:135], v[188:191], v[16:19]
	v_mfma_f32_16x16x32_bf16 v[12:15], v[140:143], v[188:191], v[12:15]
	v_mfma_f32_16x16x32_bf16 v[64:67], v[136:139], v[168:171], v[64:67]
	v_mfma_f32_16x16x32_bf16 v[60:63], v[144:147], v[168:171], v[60:63]
	v_mfma_f32_16x16x32_bf16 v[48:51], v[136:139], v[176:179], v[48:51]
	v_mfma_f32_16x16x32_bf16 v[44:47], v[144:147], v[176:179], v[44:47]
	v_mfma_f32_16x16x32_bf16 v[32:35], v[136:139], v[184:187], v[32:35]
	v_mfma_f32_16x16x32_bf16 v[28:31], v[144:147], v[184:187], v[28:31]
	v_mfma_f32_16x16x32_bf16 v[16:19], v[136:139], v[192:195], v[16:19]
	v_mfma_f32_16x16x32_bf16 v[12:15], v[144:147], v[192:195], v[12:15]
	v_mfma_f32_16x16x32_bf16 v[56:59], v[148:151], v[164:167], v[56:59]
	v_mfma_f32_16x16x32_bf16 v[52:55], v[156:159], v[164:167], v[52:55]
	v_mfma_f32_16x16x32_bf16 v[40:43], v[148:151], v[172:175], v[40:43]
	v_mfma_f32_16x16x32_bf16 v[36:39], v[156:159], v[172:175], v[36:39]
	v_mfma_f32_16x16x32_bf16 v[24:27], v[148:151], v[180:183], v[24:27]
	v_mfma_f32_16x16x32_bf16 v[20:23], v[156:159], v[180:183], v[20:23]
	v_mfma_f32_16x16x32_bf16 v[8:11], v[148:151], v[188:191], v[8:11]
	v_mfma_f32_16x16x32_bf16 v[2:5], v[156:159], v[188:191], v[4:7]
	v_mfma_f32_16x16x32_bf16 v[56:59], v[152:155], v[168:171], v[56:59]
	v_mfma_f32_16x16x32_bf16 v[52:55], v[160:163], v[168:171], v[52:55]
	v_mfma_f32_16x16x32_bf16 v[40:43], v[152:155], v[176:179], v[40:43]
	v_mfma_f32_16x16x32_bf16 v[36:39], v[160:163], v[176:179], v[36:39]
	v_mfma_f32_16x16x32_bf16 v[24:27], v[152:155], v[184:187], v[24:27]
	v_mfma_f32_16x16x32_bf16 v[20:23], v[160:163], v[184:187], v[20:23]
	v_mfma_f32_16x16x32_bf16 v[8:11], v[152:155], v[192:195], v[8:11]
	v_mfma_f32_16x16x32_bf16 v[2:5], v[160:163], v[192:195], v[2:5]
	s_barrier
	s_add_i32 s94, 0, 0x18000
	v_add_u32_e32 v0, s94, v205
	s_add_i32 s95, 0, 0x1c000
	ds_read_b128 v[132:135], v0
	ds_read_b128 v[136:139], v0 offset:1024
	ds_read_b128 v[140:143], v0 offset:2048
	ds_read_b128 v[144:147], v0 offset:3072
	v_add_u32_e32 v0, s95, v205
	ds_read_b128 v[148:151], v0
	ds_read_b128 v[152:155], v0 offset:1024
	ds_read_b128 v[156:159], v0 offset:2048
	ds_read_b128 v[160:163], v0 offset:3072
	s_mov_b32 m0, s68
	s_nop 0
	global_load_lds_dwordx4 v[244:245], off
	s_mov_b32 m0, s69
	s_nop 0
	global_load_lds_dwordx4 v[246:247], off
	s_add_u32 s54, s54, 0x80000
	s_addc_u32 s55, s55, 0
	s_mov_b32 m0, s70
	v_lshl_add_u64 v[6:7], s[54:55], 0, v[210:211]
	ds_read_b128 v[164:167], v209 offset:32768
	ds_read_b128 v[168:171], v209 offset:33792
	ds_read_b128 v[172:175], v209 offset:34816
	ds_read_b128 v[176:179], v209 offset:35840
	ds_read_b128 v[180:183], v209 offset:36864
	ds_read_b128 v[184:187], v209 offset:37888
	ds_read_b128 v[188:191], v209 offset:38912
	ds_read_b128 v[192:195], v209 offset:39936
	global_load_lds_dwordx4 v[6:7], off
	v_lshl_add_u64 v[6:7], s[54:55], 0, v[214:215]
	s_mov_b32 m0, s71
	s_nop 0
	global_load_lds_dwordx4 v[6:7], off
	s_nop 0
	s_waitcnt lgkmcnt(0)
	s_barrier
; #define PG8_STAGE(bufoff, gbase, voff) do { _Pragma("unroll") for (int _i = 0; _i < 2; ++_i) \
;         __builtin_amdgcn_global_load_lds((const unsigned*)((const char*)(gbase) + (voff)[_i]), (LAS unsigned*)(lds + (bufoff) + ldsw + _i * 8192), 16, 0, 0); } while (0)
; #define PG8_LDA(dst, b, h) do { _Pragma("unroll") for (int m = 0; m < 4; ++m) _Pragma("unroll") for (int k = 0; k < 2; ++k) dst[m][k] = *(const LAS bf16x8*)(lds + PG8_SA(b, h) + aoff + m * 2048 + k * 1024); } while (0)
; #define PG8_MMA(ai, bj, At, Bt) do { __builtin_amdgcn_s_setprio(1); _Pragma("unroll") for (int m = 0; m < 4; ++m) _Pragma("unroll") for (int n = 0; n < 2; ++n) _Pragma("unroll") for (int k = 0; k < 2; ++k) \
;         acc[ai][bj][m][n] = __builtin_amdgcn_mfma_f32_16x16x32_bf16(Bt[n][k], At[m][k], acc[ai][bj][m][n], 0, 0, 0); __builtin_amdgcn_s_setprio(0); } while (0)
; #define PG8_WAIT_V(n) asm volatile("s_waitcnt vmcnt(" #n ")" ::: "memory")
; #define PG8_WAIT_L(n) asm volatile("s_waitcnt lgkmcnt(" #n ")" ::: "memory")
; #define PG8_BAR __builtin_amdgcn_s_barrier()
; #define PG8_SCHED __builtin_amdgcn_sched_barrier(0)
; template <class Epi, bool ALIGN_EPI>
; __device__ __forceinline__ void gemm_phase(LAS unsigned char* lds, const int tid, const Gemm g, const StaticOrder& S, const Epi& E) {
;     ...
;             PG8_WAIT_V(8); PG8_WAIT_L(0); PG8_BAR; PG8_MMA(0, 0, At, B0); PG8_MMA(0, 1, At, B1); PG8_BAR; PG8_SCHED;
;             PG8_LDA(At, 1, 1); PG8_STAGE(PG8_SB(1, 0), b3, voffB); PG8_STAGE(PG8_SB(1, 1), b3 + hstepB, voffB); PG8_STAGE(PG8_SA(1, 0), a3, voffA);
;             PG8_WAIT_V(8); PG8_WAIT_L(0); PG8_BAR; PG8_MMA(1, 0, At, B0); PG8_MMA(1, 1, At, B1); PG8_BAR; PG8_SCHED;
;         }
	v_mfma_f32_16x16x32_bf16 v[128:131], v[132:135], v[164:167], v[128:131]
	v_mfma_f32_16x16x32_bf16 v[124:127], v[140:143], v[164:167], v[124:127]
	v_mfma_f32_16x16x32_bf16 v[112:115], v[132:135], v[172:175], v[112:115]
	v_mfma_f32_16x16x32_bf16 v[108:111], v[140:143], v[172:175], v[108:111]
	v_mfma_f32_16x16x32_bf16 v[96:99], v[132:135], v[180:183], v[96:99]
	v_mfma_f32_16x16x32_bf16 v[92:95], v[140:143], v[180:183], v[92:95]
	v_mfma_f32_16x16x32_bf16 v[80:83], v[132:135], v[188:191], v[80:83]
	v_mfma_f32_16x16x32_bf16 v[76:79], v[140:143], v[188:191], v[76:79]
	v_mfma_f32_16x16x32_bf16 v[128:131], v[136:139], v[168:171], v[128:131]
	v_mfma_f32_16x16x32_bf16 v[124:127], v[144:147], v[168:171], v[124:127]
	v_mfma_f32_16x16x32_bf16 v[112:115], v[136:139], v[176:179], v[112:115]
	v_mfma_f32_16x16x32_bf16 v[108:111], v[144:147], v[176:179], v[108:111]
	v_mfma_f32_16x16x32_bf16 v[96:99], v[136:139], v[184:187], v[96:99]
	v_mfma_f32_16x16x32_bf16 v[92:95], v[144:147], v[184:187], v[92:95]
	v_mfma_f32_16x16x32_bf16 v[80:83], v[136:139], v[192:195], v[80:83]
	v_mfma_f32_16x16x32_bf16 v[76:79], v[144:147], v[192:195], v[76:79]
	v_mfma_f32_16x16x32_bf16 v[120:123], v[148:151], v[164:167], v[120:123]
	v_mfma_f32_16x16x32_bf16 v[116:119], v[156:159], v[164:167], v[116:119]
	v_mfma_f32_16x16x32_bf16 v[104:107], v[148:151], v[172:175], v[104:107]
	v_mfma_f32_16x16x32_bf16 v[100:103], v[156:159], v[172:175], v[100:103]
	v_mfma_f32_16x16x32_bf16 v[88:91], v[148:151], v[180:183], v[88:91]
	v_mfma_f32_16x16x32_bf16 v[84:87], v[156:159], v[180:183], v[84:87]
	v_mfma_f32_16x16x32_bf16 v[72:75], v[148:151], v[188:191], v[72:75]
	v_mfma_f32_16x16x32_bf16 v[68:71], v[156:159], v[188:191], v[68:71]
	v_mfma_f32_16x16x32_bf16 v[120:123], v[152:155], v[168:171], v[120:123]
	v_mfma_f32_16x16x32_bf16 v[116:119], v[160:163], v[168:171], v[116:119]
	v_mfma_f32_16x16x32_bf16 v[104:107], v[152:155], v[176:179], v[104:107]
	v_mfma_f32_16x16x32_bf16 v[100:103], v[160:163], v[176:179], v[100:103]
	v_mfma_f32_16x16x32_bf16 v[88:91], v[152:155], v[184:187], v[88:91]
	v_mfma_f32_16x16x32_bf16 v[84:87], v[160:163], v[184:187], v[84:87]
	v_mfma_f32_16x16x32_bf16 v[72:75], v[152:155], v[192:195], v[72:75]
	v_mfma_f32_16x16x32_bf16 v[68:71], v[160:163], v[192:195], v[68:71]
	s_barrier
	s_add_i32 s54, s94, s67
	v_lshl_add_u64 v[6:7], v[240:241], 0, s[42:43]
	s_mov_b32 m0, s54
	ds_read_b128 v[164:167], v209 offset:49152
	ds_read_b128 v[168:171], v209 offset:50176
	ds_read_b128 v[172:175], v209 offset:51200
	ds_read_b128 v[176:179], v209 offset:52224
	ds_read_b128 v[180:183], v209 offset:53248
	ds_read_b128 v[184:187], v209 offset:54272
	ds_read_b128 v[188:191], v209 offset:55296
	ds_read_b128 v[192:195], v209 offset:56320
	global_load_lds_dwordx4 v[6:7], off
	s_add_i32 m0, s54, 0x2000
	s_add_u32 s34, s34, 0x80080
	v_lshl_add_u64 v[6:7], v[242:243], 0, s[42:43]
	s_addc_u32 s35, s35, 0
	s_add_i32 s54, s95, s67
	global_load_lds_dwordx4 v[6:7], off
	v_lshl_add_u64 v[6:7], s[34:35], 0, v[212:213]
	s_mov_b32 m0, s54
	s_nop 0
	global_load_lds_dwordx4 v[6:7], off
	v_lshl_add_u64 v[6:7], s[34:35], 0, v[216:217]
	s_add_i32 m0, s54, 0x2000
	s_nop 0
	global_load_lds_dwordx4 v[6:7], off
	s_waitcnt vmcnt(4)
	s_waitcnt lgkmcnt(0)
	s_barrier
	v_mfma_f32_16x16x32_bf16 v[64:67], v[132:135], v[164:167], v[64:67]
	v_mfma_f32_16x16x32_bf16 v[60:63], v[140:143], v[164:167], v[60:63]
	v_mfma_f32_16x16x32_bf16 v[48:51], v[132:135], v[172:175], v[48:51]
	v_mfma_f32_16x16x32_bf16 v[44:47], v[140:143], v[172:175], v[44:47]
	v_mfma_f32_16x16x32_bf16 v[32:35], v[132:135], v[180:183], v[32:35]
	v_mfma_f32_16x16x32_bf16 v[28:31], v[140:143], v[180:183], v[28:31]
	v_mfma_f32_16x16x32_bf16 v[16:19], v[132:135], v[188:191], v[16:19]
	v_mfma_f32_16x16x32_bf16 v[12:15], v[140:143], v[188:191], v[12:15]
	v_mfma_f32_16x16x32_bf16 v[64:67], v[136:139], v[168:171], v[64:67]
	v_mfma_f32_16x16x32_bf16 v[60:63], v[144:147], v[168:171], v[60:63]
	v_mfma_f32_16x16x32_bf16 v[48:51], v[136:139], v[176:179], v[48:51]
	v_mfma_f32_16x16x32_bf16 v[44:47], v[144:147], v[176:179], v[44:47]
	v_mfma_f32_16x16x32_bf16 v[32:35], v[136:139], v[184:187], v[32:35]
	v_mfma_f32_16x16x32_bf16 v[28:31], v[144:147], v[184:187], v[28:31]
	v_mfma_f32_16x16x32_bf16 v[16:19], v[136:139], v[192:195], v[16:19]
	v_mfma_f32_16x16x32_bf16 v[12:15], v[144:147], v[192:195], v[12:15]
	v_mfma_f32_16x16x32_bf16 v[56:59], v[148:151], v[164:167], v[56:59]
	v_mfma_f32_16x16x32_bf16 v[52:55], v[156:159], v[164:167], v[52:55]
	v_mfma_f32_16x16x32_bf16 v[40:43], v[148:151], v[172:175], v[40:43]
	v_mfma_f32_16x16x32_bf16 v[36:39], v[156:159], v[172:175], v[36:39]
	v_mfma_f32_16x16x32_bf16 v[24:27], v[148:151], v[180:183], v[24:27]
	v_mfma_f32_16x16x32_bf16 v[20:23], v[156:159], v[180:183], v[20:23]
	v_mfma_f32_16x16x32_bf16 v[6:9], v[148:151], v[188:191], v[8:11]
	v_mfma_f32_16x16x32_bf16 v[2:5], v[156:159], v[188:191], v[2:5]
	v_mfma_f32_16x16x32_bf16 v[56:59], v[152:155], v[168:171], v[56:59]
	v_mfma_f32_16x16x32_bf16 v[52:55], v[160:163], v[168:171], v[52:55]
	v_mfma_f32_16x16x32_bf16 v[40:43], v[152:155], v[176:179], v[40:43]
	v_mfma_f32_16x16x32_bf16 v[36:39], v[160:163], v[176:179], v[36:39]
	v_mfma_f32_16x16x32_bf16 v[24:27], v[152:155], v[184:187], v[24:27]
	v_mfma_f32_16x16x32_bf16 v[20:23], v[160:163], v[184:187], v[20:23]
	v_mfma_f32_16x16x32_bf16 v[8:11], v[152:155], v[192:195], v[6:9]
	v_mfma_f32_16x16x32_bf16 v[4:7], v[160:163], v[192:195], v[2:5]
	s_barrier
	s_add_u32 s92, s92, 0x400
	s_addc_u32 s93, s93, 0
	s_add_u32 s21, s21, 0x100
	s_addc_u32 s36, s36, 0
	s_add_u32 s30, s30, 0x100
	s_addc_u32 s31, s31, 0
	s_cmp_ge_u32 s5, s19
	s_cbranch_scc1 .LBB0_266

; #define PG8_STAGE(bufoff, gbase, voff) do { _Pragma("unroll") for (int _i = 0; _i < 2; ++_i) \
;         __builtin_amdgcn_global_load_lds((const unsigned*)((const char*)(gbase) + (voff)[_i]), (LAS unsigned*)(lds + (bufoff) + ldsw + _i * 8192), 16, 0, 0); } while (0)
; #define PG8_LDA(dst, b, h) do { _Pragma("unroll") for (int m = 0; m < 4; ++m) _Pragma("unroll") for (int k = 0; k < 2; ++k) dst[m][k] = *(const LAS bf16x8*)(lds + PG8_SA(b, h) + aoff + m * 2048 + k * 1024); } while (0)
; #define PG8_LDB(dst, b, h) do { _Pragma("unroll") for (int n = 0; n < 2; ++n) _Pragma("unroll") for (int k = 0; k < 2; ++k) dst[n][k] = *(const LAS bf16x8*)(lds + PG8_SB(b, h) + boff + n * 2048 + k * 1024); } while (0)
; #define PG8_MMA(ai, bj, At, Bt) do { __builtin_amdgcn_s_setprio(1); _Pragma("unroll") for (int m = 0; m < 4; ++m) _Pragma("unroll") for (int n = 0; n < 2; ++n) _Pragma("unroll") for (int k = 0; k < 2; ++k) \
;         acc[ai][bj][m][n] = __builtin_amdgcn_mfma_f32_16x16x32_bf16(Bt[n][k], At[m][k], acc[ai][bj][m][n], 0, 0, 0); __builtin_amdgcn_s_setprio(0); } while (0)
; #define PG8_WAIT_V(n) asm volatile("s_waitcnt vmcnt(" #n ")" ::: "memory")
; #define PG8_WAIT_L(n) asm volatile("s_waitcnt lgkmcnt(" #n ")" ::: "memory")
; #define PG8_BAR __builtin_amdgcn_s_barrier()
; #define PG8_SCHED __builtin_amdgcn_sched_barrier(0)
; template <class Epi, bool ALIGN_EPI>
; __device__ __forceinline__ void gemm_phase(LAS unsigned char* lds, const int tid, const Gemm g, const StaticOrder& S, const Epi& E) {
;     ...
;             PG8_LDB(B0, 0, 0); PG8_LDB(B1, 0, 1); PG8_SCHED; PG8_LDA(At, 0, 0); PG8_STAGE(PG8_SA(1, 1), a1 + hstepA, voffA);
;             PG8_WAIT_V(8); PG8_WAIT_L(0); PG8_BAR; PG8_MMA(0, 0, At, B0); PG8_MMA(0, 1, At, B1); PG8_BAR; PG8_SCHED;
;             PG8_LDA(At, 0, 1); PG8_STAGE(PG8_SB(0, 0), b2, voffB); PG8_STAGE(PG8_SB(0, 1), b2 + hstepB, voffB); PG8_STAGE(PG8_SA(0, 0), a2, voffA);
;             PG8_WAIT_V(8); PG8_WAIT_L(0); PG8_BAR; PG8_MMA(1, 0, At, B0); PG8_MMA(1, 1, At, B1); PG8_BAR; PG8_SCHED;
.LBB0_667:
	s_add_u32 s22, s20, 0xfff80080
	s_addc_u32 s23, s21, -1
	s_add_i32 s49, 0, 0x10000
	s_cmp_eq_u32 s19, 28
	s_cselect_b32 s25, s15, s23
	s_cselect_b32 s24, s14, s22
	v_add_u32_e32 v0, s49, v173
	s_cselect_b32 s23, s17, s13
	s_cselect_b32 s22, s16, s11
	s_add_i32 s52, 0, 0x14000
	ds_read_b128 v[130:133], v0
	ds_read_b128 v[134:137], v0 offset:1024
	ds_read_b128 v[138:141], v0 offset:2048
	ds_read_b128 v[142:145], v0 offset:3072
	v_add_u32_e32 v0, s52, v173
	ds_read_b128 v[158:161], v0
	ds_read_b128 v[162:165], v0 offset:1024
	ds_read_b128 v[166:169], v0 offset:2048
	ds_read_b128 v[178:181], v0 offset:3072
	v_lshl_add_u64 v[170:171], s[20:21], 0, v[156:157]
	s_add_i32 m0, s28, 0xc000
	ds_read_b128 v[182:185], v176
	ds_read_b128 v[186:189], v176 offset:1024
	ds_read_b128 v[190:193], v176 offset:2048
	ds_read_b128 v[208:211], v176 offset:3072
	ds_read_b128 v[212:215], v176 offset:4096
	ds_read_b128 v[216:219], v176 offset:5120
	ds_read_b128 v[220:223], v176 offset:6144
	ds_read_b128 v[240:243], v176 offset:7168
	global_load_lds_dwordx4 v[170:171], off
	v_lshl_add_u64 v[170:171], s[20:21], 0, v[154:155]
	s_add_i32 m0, s28, 0xe000
	s_nop 0
	global_load_lds_dwordx4 v[170:171], off
	s_sub_u32 s98, s20, 0x80000
	s_subb_u32 s99, s21, 0
	v_lshl_add_u64 v[170:171], s[98:99], 0, v[156:157]
	s_mov_b32 m0, s34
	s_nop 0
	global_load_lds_dwordx4 v[170:171], off
	v_lshl_add_u64 v[170:171], s[98:99], 0, v[154:155]
	s_mov_b32 m0, s35
	s_nop 0
	global_load_lds_dwordx4 v[170:171], off
	s_nop 0
	s_waitcnt lgkmcnt(0)
	s_barrier
	v_mfma_f32_16x16x32_bf16 v[126:129], v[130:133], v[182:185], v[126:129]
	v_mfma_f32_16x16x32_bf16 v[122:125], v[138:141], v[182:185], v[122:125]
	v_mfma_f32_16x16x32_bf16 v[118:121], v[130:133], v[190:193], v[118:121]
	v_mfma_f32_16x16x32_bf16 v[114:117], v[138:141], v[190:193], v[114:117]
	v_mfma_f32_16x16x32_bf16 v[102:105], v[130:133], v[212:215], v[102:105]
	v_mfma_f32_16x16x32_bf16 v[98:101], v[138:141], v[212:215], v[98:101]
	v_mfma_f32_16x16x32_bf16 v[86:89], v[130:133], v[220:223], v[86:89]
	v_mfma_f32_16x16x32_bf16 v[82:85], v[138:141], v[220:223], v[82:85]
	v_mfma_f32_16x16x32_bf16 v[126:129], v[134:137], v[186:189], v[126:129]
	v_mfma_f32_16x16x32_bf16 v[122:125], v[142:145], v[186:189], v[122:125]
	v_mfma_f32_16x16x32_bf16 v[118:121], v[134:137], v[208:211], v[118:121]
	v_mfma_f32_16x16x32_bf16 v[114:117], v[142:145], v[208:211], v[114:117]
	v_mfma_f32_16x16x32_bf16 v[102:105], v[134:137], v[216:219], v[102:105]
	v_mfma_f32_16x16x32_bf16 v[98:101], v[142:145], v[216:219], v[98:101]
	v_mfma_f32_16x16x32_bf16 v[86:89], v[134:137], v[240:243], v[86:89]
	v_mfma_f32_16x16x32_bf16 v[82:85], v[142:145], v[240:243], v[82:85]
	v_mfma_f32_16x16x32_bf16 v[110:113], v[158:161], v[182:185], v[110:113]
	v_mfma_f32_16x16x32_bf16 v[106:109], v[166:169], v[182:185], v[106:109]
	v_mfma_f32_16x16x32_bf16 v[94:97], v[158:161], v[190:193], v[94:97]
	v_mfma_f32_16x16x32_bf16 v[90:93], v[166:169], v[190:193], v[90:93]
	v_mfma_f32_16x16x32_bf16 v[78:81], v[158:161], v[212:215], v[78:81]
	v_mfma_f32_16x16x32_bf16 v[74:77], v[166:169], v[212:215], v[74:77]
	v_mfma_f32_16x16x32_bf16 v[70:73], v[158:161], v[220:223], v[70:73]
	v_mfma_f32_16x16x32_bf16 v[66:69], v[166:169], v[220:223], v[66:69]
	v_mfma_f32_16x16x32_bf16 v[110:113], v[162:165], v[186:189], v[110:113]
	v_mfma_f32_16x16x32_bf16 v[106:109], v[178:181], v[186:189], v[106:109]
	v_mfma_f32_16x16x32_bf16 v[94:97], v[162:165], v[208:211], v[94:97]
	v_mfma_f32_16x16x32_bf16 v[90:93], v[178:181], v[208:211], v[90:93]
	v_mfma_f32_16x16x32_bf16 v[78:81], v[162:165], v[216:219], v[78:81]
	v_mfma_f32_16x16x32_bf16 v[74:77], v[178:181], v[216:219], v[74:77]
	v_mfma_f32_16x16x32_bf16 v[70:73], v[162:165], v[240:243], v[70:73]
	v_mfma_f32_16x16x32_bf16 v[66:69], v[178:181], v[240:243], v[66:69]
	s_barrier
	s_add_i32 s49, s49, s27
	v_lshl_add_u64 v[170:171], s[22:23], 0, v[148:149]
	s_mov_b32 m0, s49
	ds_read_b128 v[182:185], v176 offset:16384
	ds_read_b128 v[186:189], v176 offset:17408
	ds_read_b128 v[190:193], v176 offset:18432
	ds_read_b128 v[208:211], v176 offset:19456
	ds_read_b128 v[212:215], v176 offset:20480
	ds_read_b128 v[216:219], v176 offset:21504
	ds_read_b128 v[220:223], v176 offset:22528
	ds_read_b128 v[240:243], v176 offset:23552
	global_load_lds_dwordx4 v[170:171], off
	s_add_i32 m0, s49, 0x2000
	s_add_u32 s54, s22, 0x80000
	v_lshl_add_u64 v[194:195], s[22:23], 0, v[152:153]
	s_addc_u32 s55, s23, 0
	s_add_i32 s49, s52, s27
	global_load_lds_dwordx4 v[194:195], off
	v_lshl_add_u64 v[224:225], s[54:55], 0, v[148:149]
	s_mov_b32 m0, s49
	v_lshl_add_u64 v[244:245], s[24:25], 0, v[150:151]
	global_load_lds_dwordx4 v[224:225], off
	v_lshl_add_u64 v[224:225], s[54:55], 0, v[152:153]
	s_add_i32 m0, s49, 0x2000
	s_nop 0
	global_load_lds_dwordx4 v[224:225], off
	v_lshl_add_u64 v[224:225], s[24:25], 0, v[146:147]
	s_waitcnt vmcnt(4)
	s_waitcnt lgkmcnt(0)
	s_barrier
; #define PG8_STAGE(bufoff, gbase, voff) do { _Pragma("unroll") for (int _i = 0; _i < 2; ++_i) \
;         __builtin_amdgcn_global_load_lds((const unsigned*)((const char*)(gbase) + (voff)[_i]), (LAS unsigned*)(lds + (bufoff) + ldsw + _i * 8192), 16, 0, 0); } while (0)
; #define PG8_LDA(dst, b, h) do { _Pragma("unroll") for (int m = 0; m < 4; ++m) _Pragma("unroll") for (int k = 0; k < 2; ++k) dst[m][k] = *(const LAS bf16x8*)(lds + PG8_SA(b, h) + aoff + m * 2048 + k * 1024); } while (0)
; #define PG8_LDB(dst, b, h) do { _Pragma("unroll") for (int n = 0; n < 2; ++n) _Pragma("unroll") for (int k = 0; k < 2; ++k) dst[n][k] = *(const LAS bf16x8*)(lds + PG8_SB(b, h) + boff + n * 2048 + k * 1024); } while (0)
; #define PG8_MMA(ai, bj, At, Bt) do { __builtin_amdgcn_s_setprio(1); _Pragma("unroll") for (int m = 0; m < 4; ++m) _Pragma("unroll") for (int n = 0; n < 2; ++n) _Pragma("unroll") for (int k = 0; k < 2; ++k) \
;         acc[ai][bj][m][n] = __builtin_amdgcn_mfma_f32_16x16x32_bf16(Bt[n][k], At[m][k], acc[ai][bj][m][n], 0, 0, 0); __builtin_amdgcn_s_setprio(0); } while (0)
; #define PG8_WAIT_V(n) asm volatile("s_waitcnt vmcnt(" #n ")" ::: "memory")
; #define PG8_WAIT_L(n) asm volatile("s_waitcnt lgkmcnt(" #n ")" ::: "memory")
; #define PG8_BAR __builtin_amdgcn_s_barrier()
; #define PG8_SCHED __builtin_amdgcn_sched_barrier(0)
; template <class Epi, bool ALIGN_EPI>
; __device__ __forceinline__ void gemm_phase(LAS unsigned char* lds, const int tid, const Gemm g, const StaticOrder& S, const Epi& E) {
;     ...
;             PG8_WAIT_V(8); PG8_WAIT_L(0); PG8_BAR; PG8_MMA(1, 0, At, B0); PG8_MMA(1, 1, At, B1); PG8_BAR; PG8_SCHED;
;             PG8_LDB(B0, 1, 0); PG8_LDB(B1, 1, 1); PG8_SCHED; PG8_LDA(At, 1, 0); PG8_STAGE(PG8_SA(0, 1), a2 + hstepA, voffA);
;             PG8_WAIT_V(8); PG8_WAIT_L(0); PG8_BAR; PG8_MMA(0, 0, At, B0); PG8_MMA(0, 1, At, B1); PG8_BAR; PG8_SCHED;
	v_mfma_f32_16x16x32_bf16 v[62:65], v[130:133], v[182:185], v[62:65]
	v_mfma_f32_16x16x32_bf16 v[58:61], v[138:141], v[182:185], v[58:61]
	v_mfma_f32_16x16x32_bf16 v[54:57], v[130:133], v[190:193], v[54:57]
	v_mfma_f32_16x16x32_bf16 v[50:53], v[138:141], v[190:193], v[50:53]
	v_mfma_f32_16x16x32_bf16 v[38:41], v[130:133], v[212:215], v[38:41]
	v_mfma_f32_16x16x32_bf16 v[34:37], v[138:141], v[212:215], v[34:37]
	v_mfma_f32_16x16x32_bf16 v[22:25], v[130:133], v[220:223], v[22:25]
	v_mfma_f32_16x16x32_bf16 v[18:21], v[138:141], v[220:223], v[18:21]
	v_mfma_f32_16x16x32_bf16 v[62:65], v[134:137], v[186:189], v[62:65]
	v_mfma_f32_16x16x32_bf16 v[58:61], v[142:145], v[186:189], v[58:61]
	v_mfma_f32_16x16x32_bf16 v[54:57], v[134:137], v[208:211], v[54:57]
	v_mfma_f32_16x16x32_bf16 v[50:53], v[142:145], v[208:211], v[50:53]
	v_mfma_f32_16x16x32_bf16 v[38:41], v[134:137], v[216:219], v[38:41]
	v_mfma_f32_16x16x32_bf16 v[34:37], v[142:145], v[216:219], v[34:37]
	v_mfma_f32_16x16x32_bf16 v[22:25], v[134:137], v[240:243], v[22:25]
	v_mfma_f32_16x16x32_bf16 v[18:21], v[142:145], v[240:243], v[18:21]
	v_mfma_f32_16x16x32_bf16 v[46:49], v[158:161], v[182:185], v[46:49]
	v_mfma_f32_16x16x32_bf16 v[42:45], v[166:169], v[182:185], v[42:45]
	v_mfma_f32_16x16x32_bf16 v[30:33], v[158:161], v[190:193], v[30:33]
	v_mfma_f32_16x16x32_bf16 v[26:29], v[166:169], v[190:193], v[26:29]
	v_mfma_f32_16x16x32_bf16 v[14:17], v[158:161], v[212:215], v[14:17]
	v_mfma_f32_16x16x32_bf16 v[10:13], v[166:169], v[212:215], v[10:13]
	v_mfma_f32_16x16x32_bf16 v[6:9], v[158:161], v[220:223], v[6:9]
	v_mfma_f32_16x16x32_bf16 v[2:5], v[166:169], v[220:223], v[2:5]
	v_mfma_f32_16x16x32_bf16 v[46:49], v[162:165], v[186:189], v[46:49]
	v_mfma_f32_16x16x32_bf16 v[42:45], v[178:181], v[186:189], v[42:45]
	v_mfma_f32_16x16x32_bf16 v[30:33], v[162:165], v[208:211], v[30:33]
	v_mfma_f32_16x16x32_bf16 v[26:29], v[178:181], v[208:211], v[26:29]
	v_mfma_f32_16x16x32_bf16 v[14:17], v[162:165], v[216:219], v[14:17]
	v_mfma_f32_16x16x32_bf16 v[10:13], v[178:181], v[216:219], v[10:13]
	v_mfma_f32_16x16x32_bf16 v[6:9], v[162:165], v[240:243], v[6:9]
	v_mfma_f32_16x16x32_bf16 v[2:5], v[178:181], v[240:243], v[2:5]
	s_barrier
	s_add_i32 s49, 0, 0x18000
	v_add_u32_e32 v0, s49, v173
	s_add_i32 s52, 0, 0x1c000
	ds_read_b128 v[130:133], v0
	ds_read_b128 v[134:137], v0 offset:1024
	ds_read_b128 v[138:141], v0 offset:2048
	ds_read_b128 v[142:145], v0 offset:3072
	v_add_u32_e32 v0, s52, v173
	ds_read_b128 v[158:161], v0
	ds_read_b128 v[162:165], v0 offset:1024
	ds_read_b128 v[166:169], v0 offset:2048
	ds_read_b128 v[178:181], v0 offset:3072
	s_mov_b32 m0, s28
	s_nop 0
	global_load_lds_dwordx4 v[224:225], off
	s_mov_b32 m0, s29
	s_nop 0
	global_load_lds_dwordx4 v[244:245], off
	s_add_u32 s24, s24, 0x80000
	s_addc_u32 s25, s25, 0
	s_mov_b32 m0, s30
	v_lshl_add_u64 v[246:247], s[24:25], 0, v[146:147]
	ds_read_b128 v[182:185], v176 offset:32768
	ds_read_b128 v[186:189], v176 offset:33792
	ds_read_b128 v[190:193], v176 offset:34816
	ds_read_b128 v[208:211], v176 offset:35840
	ds_read_b128 v[212:215], v176 offset:36864
	ds_read_b128 v[216:219], v176 offset:37888
	ds_read_b128 v[220:223], v176 offset:38912
	ds_read_b128 v[240:243], v176 offset:39936
	global_load_lds_dwordx4 v[246:247], off
	v_lshl_add_u64 v[246:247], s[24:25], 0, v[150:151]
	s_mov_b32 m0, s31
	s_nop 0
	global_load_lds_dwordx4 v[246:247], off
	s_nop 0
	s_waitcnt lgkmcnt(0)
	s_barrier
	v_mfma_f32_16x16x32_bf16 v[126:129], v[130:133], v[182:185], v[126:129]
	v_mfma_f32_16x16x32_bf16 v[122:125], v[138:141], v[182:185], v[122:125]
	v_mfma_f32_16x16x32_bf16 v[118:121], v[130:133], v[190:193], v[118:121]
	v_mfma_f32_16x16x32_bf16 v[114:117], v[138:141], v[190:193], v[114:117]
	v_mfma_f32_16x16x32_bf16 v[102:105], v[130:133], v[212:215], v[102:105]
	v_mfma_f32_16x16x32_bf16 v[98:101], v[138:141], v[212:215], v[98:101]
	v_mfma_f32_16x16x32_bf16 v[86:89], v[130:133], v[220:223], v[86:89]
	v_mfma_f32_16x16x32_bf16 v[82:85], v[138:141], v[220:223], v[82:85]
	v_mfma_f32_16x16x32_bf16 v[126:129], v[134:137], v[186:189], v[126:129]
	v_mfma_f32_16x16x32_bf16 v[122:125], v[142:145], v[186:189], v[122:125]
	v_mfma_f32_16x16x32_bf16 v[118:121], v[134:137], v[208:211], v[118:121]
	v_mfma_f32_16x16x32_bf16 v[114:117], v[142:145], v[208:211], v[114:117]
	v_mfma_f32_16x16x32_bf16 v[102:105], v[134:137], v[216:219], v[102:105]
	v_mfma_f32_16x16x32_bf16 v[98:101], v[142:145], v[216:219], v[98:101]
	v_mfma_f32_16x16x32_bf16 v[86:89], v[134:137], v[240:243], v[86:89]
	v_mfma_f32_16x16x32_bf16 v[82:85], v[142:145], v[240:243], v[82:85]
	v_mfma_f32_16x16x32_bf16 v[110:113], v[158:161], v[182:185], v[110:113]
	v_mfma_f32_16x16x32_bf16 v[106:109], v[166:169], v[182:185], v[106:109]
	v_mfma_f32_16x16x32_bf16 v[94:97], v[158:161], v[190:193], v[94:97]
	v_mfma_f32_16x16x32_bf16 v[90:93], v[166:169], v[190:193], v[90:93]
	v_mfma_f32_16x16x32_bf16 v[78:81], v[158:161], v[212:215], v[78:81]
	v_mfma_f32_16x16x32_bf16 v[74:77], v[166:169], v[212:215], v[74:77]
	v_mfma_f32_16x16x32_bf16 v[70:73], v[158:161], v[220:223], v[70:73]
	v_mfma_f32_16x16x32_bf16 v[66:69], v[166:169], v[220:223], v[66:69]
	v_mfma_f32_16x16x32_bf16 v[110:113], v[162:165], v[186:189], v[110:113]
	v_mfma_f32_16x16x32_bf16 v[106:109], v[178:181], v[186:189], v[106:109]
	v_mfma_f32_16x16x32_bf16 v[94:97], v[162:165], v[208:211], v[94:97]
	v_mfma_f32_16x16x32_bf16 v[90:93], v[178:181], v[208:211], v[90:93]
	v_mfma_f32_16x16x32_bf16 v[78:81], v[162:165], v[216:219], v[78:81]
	v_mfma_f32_16x16x32_bf16 v[74:77], v[178:181], v[216:219], v[74:77]
	v_mfma_f32_16x16x32_bf16 v[70:73], v[162:165], v[240:243], v[70:73]
	v_mfma_f32_16x16x32_bf16 v[66:69], v[178:181], v[240:243], v[66:69]
	s_barrier
; #define GAS __attribute__((address_space(1)))
; #define PG8_STAGE(bufoff, gbase, voff) do { _Pragma("unroll") for (int _i = 0; _i < 2; ++_i) \
;         __builtin_amdgcn_global_load_lds((const unsigned*)((const char*)(gbase) + (voff)[_i]), (LAS unsigned*)(lds + (bufoff) + ldsw + _i * 8192), 16, 0, 0); } while (0)
; #define PG8_LDA(dst, b, h) do { _Pragma("unroll") for (int m = 0; m < 4; ++m) _Pragma("unroll") for (int k = 0; k < 2; ++k) dst[m][k] = *(const LAS bf16x8*)(lds + PG8_SA(b, h) + aoff + m * 2048 + k * 1024); } while (0)
; #define PG8_MMA(ai, bj, At, Bt) do { __builtin_amdgcn_s_setprio(1); _Pragma("unroll") for (int m = 0; m < 4; ++m) _Pragma("unroll") for (int n = 0; n < 2; ++n) _Pragma("unroll") for (int k = 0; k < 2; ++k) \
;         acc[ai][bj][m][n] = __builtin_amdgcn_mfma_f32_16x16x32_bf16(Bt[n][k], At[m][k], acc[ai][bj][m][n], 0, 0, 0); __builtin_amdgcn_s_setprio(0); } while (0)
; #define PG8_WAIT_V(n) asm volatile("s_waitcnt vmcnt(" #n ")" ::: "memory")
; #define PG8_WAIT_L(n) asm volatile("s_waitcnt lgkmcnt(" #n ")" ::: "memory")
; #define PG8_BAR __builtin_amdgcn_s_barrier()
; #define PG8_SCHED __builtin_amdgcn_sched_barrier(0)
; template <class Epi, bool ALIGN_EPI>
; __device__ __forceinline__ void gemm_phase(LAS unsigned char* lds, const int tid, const Gemm g, const StaticOrder& S, const Epi& E) {
;     ...
;             PG8_LDA(At, 1, 1); PG8_STAGE(PG8_SB(1, 0), b3, voffB); PG8_STAGE(PG8_SB(1, 1), b3 + hstepB, voffB); PG8_STAGE(PG8_SA(1, 0), a3, voffA);
;             PG8_WAIT_V(8); PG8_WAIT_L(0); PG8_BAR; PG8_MMA(1, 0, At, B0); PG8_MMA(1, 1, At, B1); PG8_BAR; PG8_SCHED;
;         }
;     __device__ __forceinline__ void operator()(const f32x4 (&acc)[2][2][4][2], const Unit& u, int wr, int wc, int fr, int fq) const {
;     ...
;         } else {
;             const int col0 = colt - ZW + wc * 32 + 8 * fq;
;             f32x4 bv[2][2];
; #pragma unroll
;             for (int bj = 0; bj < 2; ++bj)
; #pragma unroll
;                 for (int n = 0; n < 2; ++n) bv[bj][n] = *(const GAS f32x4*)(bgate + col0 + bj * HALF + 4 * n);
	s_add_i32 s24, s49, s27
	v_lshl_add_u64 v[170:171], v[170:171], 0, s[42:43]
	s_mov_b32 m0, s24
	ds_read_b128 v[182:185], v176 offset:49152
	ds_read_b128 v[186:189], v176 offset:50176
	ds_read_b128 v[190:193], v176 offset:51200
	ds_read_b128 v[208:211], v176 offset:52224
	ds_read_b128 v[212:215], v176 offset:53248
	ds_read_b128 v[216:219], v176 offset:54272
	ds_read_b128 v[220:223], v176 offset:55296
	ds_read_b128 v[240:243], v176 offset:56320
	global_load_lds_dwordx4 v[170:171], off
	s_add_i32 m0, s24, 0x2000
	s_add_u32 s22, s22, 0x80080
	v_lshl_add_u64 v[170:171], v[194:195], 0, s[42:43]
	s_addc_u32 s23, s23, 0
	s_add_i32 s24, s52, s27
	global_load_lds_dwordx4 v[170:171], off
	v_lshl_add_u64 v[170:171], s[22:23], 0, v[148:149]
	s_mov_b32 m0, s24
	s_nop 0
	global_load_lds_dwordx4 v[170:171], off
	v_lshl_add_u64 v[170:171], s[22:23], 0, v[152:153]
	s_add_i32 m0, s24, 0x2000
	s_nop 0
	global_load_lds_dwordx4 v[170:171], off
	s_waitcnt vmcnt(4)
	s_waitcnt lgkmcnt(0)
	s_barrier
	v_mfma_f32_16x16x32_bf16 v[62:65], v[130:133], v[182:185], v[62:65]
	v_mfma_f32_16x16x32_bf16 v[58:61], v[138:141], v[182:185], v[58:61]
	v_mfma_f32_16x16x32_bf16 v[54:57], v[130:133], v[190:193], v[54:57]
	v_mfma_f32_16x16x32_bf16 v[50:53], v[138:141], v[190:193], v[50:53]
	v_mfma_f32_16x16x32_bf16 v[38:41], v[130:133], v[212:215], v[38:41]
	v_mfma_f32_16x16x32_bf16 v[34:37], v[138:141], v[212:215], v[34:37]
	v_mfma_f32_16x16x32_bf16 v[22:25], v[130:133], v[220:223], v[22:25]
	v_mfma_f32_16x16x32_bf16 v[18:21], v[138:141], v[220:223], v[18:21]
	v_mfma_f32_16x16x32_bf16 v[62:65], v[134:137], v[186:189], v[62:65]
	v_mfma_f32_16x16x32_bf16 v[58:61], v[142:145], v[186:189], v[58:61]
	v_mfma_f32_16x16x32_bf16 v[54:57], v[134:137], v[208:211], v[54:57]
	v_mfma_f32_16x16x32_bf16 v[50:53], v[142:145], v[208:211], v[50:53]
	v_mfma_f32_16x16x32_bf16 v[38:41], v[134:137], v[216:219], v[38:41]
	v_mfma_f32_16x16x32_bf16 v[34:37], v[142:145], v[216:219], v[34:37]
	v_mfma_f32_16x16x32_bf16 v[22:25], v[134:137], v[240:243], v[22:25]
	v_mfma_f32_16x16x32_bf16 v[18:21], v[142:145], v[240:243], v[18:21]
	v_mfma_f32_16x16x32_bf16 v[46:49], v[158:161], v[182:185], v[46:49]
	v_mfma_f32_16x16x32_bf16 v[42:45], v[166:169], v[182:185], v[42:45]
	v_mfma_f32_16x16x32_bf16 v[30:33], v[158:161], v[190:193], v[30:33]
	v_mfma_f32_16x16x32_bf16 v[26:29], v[166:169], v[190:193], v[26:29]
	v_mfma_f32_16x16x32_bf16 v[14:17], v[158:161], v[212:215], v[14:17]
	v_mfma_f32_16x16x32_bf16 v[10:13], v[166:169], v[212:215], v[10:13]
	v_mfma_f32_16x16x32_bf16 v[6:9], v[158:161], v[220:223], v[6:9]
	v_mfma_f32_16x16x32_bf16 v[2:5], v[166:169], v[220:223], v[2:5]
	v_mfma_f32_16x16x32_bf16 v[46:49], v[162:165], v[186:189], v[46:49]
	v_mfma_f32_16x16x32_bf16 v[42:45], v[178:181], v[186:189], v[42:45]
	v_mfma_f32_16x16x32_bf16 v[30:33], v[162:165], v[208:211], v[30:33]
	v_mfma_f32_16x16x32_bf16 v[26:29], v[178:181], v[208:211], v[26:29]
	v_mfma_f32_16x16x32_bf16 v[14:17], v[162:165], v[216:219], v[14:17]
	v_mfma_f32_16x16x32_bf16 v[10:13], v[178:181], v[216:219], v[10:13]
	v_mfma_f32_16x16x32_bf16 v[6:9], v[162:165], v[240:243], v[6:9]
	v_mfma_f32_16x16x32_bf16 v[2:5], v[178:181], v[240:243], v[2:5]
	s_barrier
	s_add_i32 s19, s19, 2
	s_add_u32 s11, s11, 0x100
	s_addc_u32 s13, s13, 0
	s_add_u32 s20, s20, 0x100
	s_addc_u32 s21, s21, 0
	s_cmp_gt_u32 s19, 29
	s_cbranch_scc0 .LBB0_667
	s_lshl_b32 s11, s41, 8
	s_cmp_gt_i32 s41, 16
	s_cbranch_scc0 .Lwin_nobias
	v_add_u32_e32 v0, s11, v175
	v_lshl_add_u64 v[134:135], v[0:1], 2, s[6:7]
	global_load_dwordx4 v[138:141], v[134:135], off offset:16
	global_load_dwordx4 v[142:145], v[134:135], off
	global_load_dwordx4 v[130:133], v[134:135], off offset:528
	s_nop 0
	global_load_dwordx4 v[134:137], v[134:135], off offset:512
